# attention epilogues (MLA, memory, SWA, DSA): four fp8 output dwords per row exchanged across lane halves with v_permlane32_swap and stored as one global_store_dwordx4 instead of four global_store_dwor
# speedup vs baseline: 1.0312x; 1.0312x over previous
; DI float bf2f(unsigned b) { return __uint_as_float(b << 16); }
; template <int DQK, int W1, int DV, int VW, int MODE> ...
;     ...
;   const float inv = __builtin_amdgcn_rcpf(xhalf_sum(l));
;   u32x2 ggv[NCB * 4];
; #pragma unroll
;   for (int cb = 0; cb < NCB; ++cb)
; #pragma unroll
;     for (int g = 0; g < 4; ++g) ggv[cb * 4 + g] = *(const u32x2*)(grow + 32 * cb + 8 * g + 4 * hi);
;   __builtin_amdgcn_sched_barrier(0);
; #pragma unroll
;   for (int cb = 0; cb < NCB; ++cb)
; #pragma unroll
;     for (int g = 0; g < 4; ++g) {
;       const int dv = 32 * cb + 8 * g + 4 * hi;
;       const u32x2 gg = ggv[cb * 4 + g];
;       float gv[4] = {bf2f(gg[0] & 0xffffu), bf2f(gg[0] >> 16), bf2f(gg[1] & 0xffffu), bf2f(gg[1] >> 16)};
;       float ov[4];
; #pragma unroll
;       for (int j = 0; j < 4; ++j) {
;         const float sg = gv[j] * __builtin_amdgcn_rcpf(1.f + __builtin_amdgcn_exp2f(-LOG2E * gv[j]));
;         ov[j] = o[cb][4 * g + j] * inv * sg;
;       }
;       *(unsigned*)((unsigned char*)yrow + dv) = pk4_fp8(ov[0] * Y_SCALE, ov[1] * Y_SCALE, ov[2] * Y_SCALE, ov[3] * Y_SCALE);
;       __builtin_amdgcn_sched_barrier(0);
;     }
.LBB0_1238:
	s_lshl_b32 s0, s27, 7
	v_lshlrev_b64 v[2:3], 13, v[184:185]
	s_ashr_i32 s1, s0, 31
	v_lshl_add_u64 v[2:3], s[6:7], 0, v[2:3]
	v_lshl_add_u64 v[2:3], s[0:1], 1, v[2:3]
	v_lshlrev_b32_e32 v0, 1, v188
	v_lshl_add_u64 v[2:3], v[2:3], 0, v[0:1]
	global_load_dwordx2 v[4:5], v[2:3], off offset:2048
	global_load_dwordx2 v[96:97], v[2:3], off offset:2064
	global_load_dwordx2 v[94:95], v[2:3], off offset:2080
	global_load_dwordx2 v[92:93], v[2:3], off offset:2096
	global_load_dwordx2 v[90:91], v[2:3], off offset:2112
	global_load_dwordx2 v[88:89], v[2:3], off offset:2128
	global_load_dwordx2 v[86:87], v[2:3], off offset:2144
	global_load_dwordx2 v[84:85], v[2:3], off offset:2160
	global_load_dwordx2 v[82:83], v[2:3], off offset:2176
	global_load_dwordx2 v[80:81], v[2:3], off offset:2192
	global_load_dwordx2 v[14:15], v[2:3], off offset:2208
	global_load_dwordx2 v[12:13], v[2:3], off offset:2224
	global_load_dwordx2 v[10:11], v[2:3], off offset:2240
	global_load_dwordx2 v[8:9], v[2:3], off offset:2256
	global_load_dwordx2 v[6:7], v[2:3], off offset:2272
	s_nop 0
	global_load_dwordx2 v[2:3], v[2:3], off offset:2288
	v_mov_b32_e32 v0, v236
	s_nop 1
	v_permlane32_swap_b32_e32 v236, v0
	v_readlane_b32 s28, v254, 27
	v_add_f32_e32 v0, v236, v0
	v_lshl_add_u64 v[98:99], s[82:83], 0, v[182:183]
	v_readlane_b32 s29, v254, 28
	v_rcp_f32_e32 v0, v0
	v_lshl_add_u64 v[98:99], v[98:99], 0, s[0:1]
	v_mov_b32_e32 v189, v1
	s_waitcnt vmcnt(15)
	v_lshlrev_b32_e32 v100, 16, v4
	v_mul_f32_e32 v102, 0xbfb8aa3b, v100
	v_exp_f32_e32 v102, v102
	v_and_b32_e32 v4, 0xffff0000, v4
	v_mul_f32_e32 v64, v64, v0
	v_lshlrev_b32_e32 v101, 16, v5
	v_add_f32_e32 v102, 1.0, v102
	v_rcp_f32_e32 v102, v102
	v_mul_f32_e32 v65, v65, v0
	v_and_b32_e32 v5, 0xffff0000, v5
	v_mul_f32_e32 v66, v66, v0
	v_mul_f32_e32 v100, v102, v100
	v_mul_f32_e32 v64, v64, v100
	v_mul_f32_e32 v100, 0xbfb8aa3b, v4
	v_exp_f32_e32 v100, v100
	v_mul_f32_e32 v64, 0x41800000, v64
	v_med3_f32 v64, v64, s93, v223
	v_add_f32_e32 v100, 1.0, v100
	v_rcp_f32_e32 v100, v100
	s_nop 0
	v_mul_f32_e32 v4, v100, v4
	v_mul_f32_e32 v4, v65, v4
	v_mul_f32_e32 v65, 0xbfb8aa3b, v101
	v_exp_f32_e32 v65, v65
	v_mul_f32_e32 v4, 0x41800000, v4
	v_med3_f32 v4, v4, s93, v223
	v_add_f32_e32 v65, 1.0, v65
	v_rcp_f32_e32 v65, v65
	s_nop 0
	v_mul_f32_e32 v65, v65, v101
	v_mul_f32_e32 v65, v66, v65
	v_mul_f32_e32 v66, 0xbfb8aa3b, v5
	v_exp_f32_e32 v66, v66
	v_mul_f32_e32 v65, 0x41800000, v65
	v_add_f32_e32 v66, 1.0, v66
	v_rcp_f32_e32 v66, v66
	s_nop 0
	v_mul_f32_e32 v5, v66, v5
	v_mul_f32_e32 v66, v67, v0
	v_mul_f32_e32 v5, v66, v5
	v_mov_b32_e32 v212, v1
	v_cvt_pk_fp8_f32 v212, v64, v4
	v_mul_f32_e32 v5, 0x41800000, v5
	v_med3_f32 v4, v65, s93, v223
	v_med3_f32 v5, v5, s93, v223
	v_cvt_pk_fp8_f32 v212, v4, v5 op_sel:[0,0,1]
	v_lshl_add_u64 v[4:5], v[98:99], 0, v[188:189]
	s_waitcnt vmcnt(14)
	v_lshlrev_b32_e32 v64, 16, v96
	v_and_b32_e32 v65, 0xffff0000, v96
	v_mul_f32_e32 v96, 0xbfb8aa3b, v64
	v_exp_f32_e32 v96, v96
	v_mul_f32_e32 v68, v68, v0
	v_lshlrev_b32_e32 v66, 16, v97
	v_and_b32_e32 v67, 0xffff0000, v97
	v_add_f32_e32 v96, 1.0, v96
	v_rcp_f32_e32 v96, v96
	s_nop 0
	v_mul_f32_e32 v64, v96, v64
	v_mul_f32_e32 v64, v68, v64
	v_mul_f32_e32 v68, 0xbfb8aa3b, v65
	v_exp_f32_e32 v68, v68
	v_mul_f32_e32 v64, 0x41800000, v64
	v_med3_f32 v64, v64, s93, v223
	v_add_f32_e32 v68, 1.0, v68
	v_rcp_f32_e32 v68, v68
	s_nop 0
	v_mul_f32_e32 v65, v68, v65
	v_mul_f32_e32 v68, v69, v0
	v_mul_f32_e32 v65, v68, v65
	v_mul_f32_e32 v68, 0xbfb8aa3b, v66
	v_exp_f32_e32 v68, v68
	v_mul_f32_e32 v65, 0x41800000, v65
	v_med3_f32 v65, v65, s93, v223
	v_add_f32_e32 v68, 1.0, v68
	v_rcp_f32_e32 v68, v68
	s_nop 0
	v_mul_f32_e32 v66, v68, v66
	v_mul_f32_e32 v68, v70, v0
	v_mul_f32_e32 v66, v68, v66
	v_mul_f32_e32 v68, 0xbfb8aa3b, v67
	v_exp_f32_e32 v68, v68
	v_mul_f32_e32 v66, 0x41800000, v66
	v_add_f32_e32 v68, 1.0, v68
	v_rcp_f32_e32 v68, v68
	s_nop 0
	v_mul_f32_e32 v67, v68, v67
	v_mul_f32_e32 v68, v71, v0
	v_mul_f32_e32 v67, v68, v67
	v_mov_b32_e32 v214, v1
	v_cvt_pk_fp8_f32 v214, v64, v65
	v_mul_f32_e32 v67, 0x41800000, v67
	v_med3_f32 v64, v66, s93, v223
	v_med3_f32 v65, v67, s93, v223
	v_cvt_pk_fp8_f32 v214, v64, v65 op_sel:[0,0,1]
	s_waitcnt vmcnt(13)
	v_lshlrev_b32_e32 v64, 16, v94
	v_mul_f32_e32 v68, 0xbfb8aa3b, v64
	v_exp_f32_e32 v68, v68
	v_and_b32_e32 v65, 0xffff0000, v94
	v_lshlrev_b32_e32 v66, 16, v95
	v_and_b32_e32 v67, 0xffff0000, v95
	v_add_f32_e32 v68, 1.0, v68
	v_rcp_f32_e32 v68, v68
	s_nop 0
	v_mul_f32_e32 v64, v68, v64
	v_mul_f32_e32 v68, v72, v0
	v_mul_f32_e32 v64, v68, v64
	v_mul_f32_e32 v68, 0xbfb8aa3b, v65
	v_exp_f32_e32 v68, v68
	v_mul_f32_e32 v64, 0x41800000, v64
	v_med3_f32 v64, v64, s93, v223
	v_add_f32_e32 v68, 1.0, v68
	v_rcp_f32_e32 v68, v68
	s_nop 0
	v_mul_f32_e32 v65, v68, v65
	v_mul_f32_e32 v68, v73, v0
	v_mul_f32_e32 v65, v68, v65
	v_mul_f32_e32 v68, 0xbfb8aa3b, v66
	v_exp_f32_e32 v68, v68
	v_mul_f32_e32 v65, 0x41800000, v65
	v_med3_f32 v65, v65, s93, v223
	v_add_f32_e32 v68, 1.0, v68
	v_rcp_f32_e32 v68, v68
	s_nop 0
	v_mul_f32_e32 v66, v68, v66
	v_mul_f32_e32 v68, v74, v0
	v_mul_f32_e32 v66, v68, v66
	v_mul_f32_e32 v68, 0xbfb8aa3b, v67
	v_exp_f32_e32 v68, v68
	v_mul_f32_e32 v66, 0x41800000, v66
	v_add_f32_e32 v68, 1.0, v68
	v_rcp_f32_e32 v68, v68
	s_nop 0
	v_mul_f32_e32 v67, v68, v67
	v_mul_f32_e32 v68, v75, v0
	v_mul_f32_e32 v67, v68, v67
	v_mov_b32_e32 v213, v1
	v_cvt_pk_fp8_f32 v213, v64, v65
	v_mul_f32_e32 v67, 0x41800000, v67
	v_med3_f32 v64, v66, s93, v223
	v_med3_f32 v65, v67, s93, v223
	v_cvt_pk_fp8_f32 v213, v64, v65 op_sel:[0,0,1]
	s_waitcnt vmcnt(12)
; DI float bf2f(unsigned b) { return __uint_as_float(b << 16); }
; template <int DQK, int W1, int DV, int VW, int MODE> ...
;     ...
; #pragma unroll
;   for (int cb = 0; cb < NCB; ++cb)
; #pragma unroll
;     for (int g = 0; g < 4; ++g) {
;       const int dv = 32 * cb + 8 * g + 4 * hi;
;       const u32x2 gg = ggv[cb * 4 + g];
;       float gv[4] = {bf2f(gg[0] & 0xffffu), bf2f(gg[0] >> 16), bf2f(gg[1] & 0xffffu), bf2f(gg[1] >> 16)};
;       float ov[4];
; #pragma unroll
;       for (int j = 0; j < 4; ++j) {
;         const float sg = gv[j] * __builtin_amdgcn_rcpf(1.f + __builtin_amdgcn_exp2f(-LOG2E * gv[j]));
;         ov[j] = o[cb][4 * g + j] * inv * sg;
;       }
;       *(unsigned*)((unsigned char*)yrow + dv) = pk4_fp8(ov[0] * Y_SCALE, ov[1] * Y_SCALE, ov[2] * Y_SCALE, ov[3] * Y_SCALE);
;       __builtin_amdgcn_sched_barrier(0);
;     }
	v_lshlrev_b32_e32 v64, 16, v92
	v_mul_f32_e32 v68, 0xbfb8aa3b, v64
	v_exp_f32_e32 v68, v68
	v_and_b32_e32 v65, 0xffff0000, v92
	v_lshlrev_b32_e32 v66, 16, v93
	v_and_b32_e32 v67, 0xffff0000, v93
	v_add_f32_e32 v68, 1.0, v68
	v_rcp_f32_e32 v68, v68
	s_nop 0
	v_mul_f32_e32 v64, v68, v64
	v_mul_f32_e32 v68, v76, v0
	v_mul_f32_e32 v64, v68, v64
	v_mul_f32_e32 v68, 0xbfb8aa3b, v65
	v_exp_f32_e32 v68, v68
	v_mul_f32_e32 v64, 0x41800000, v64
	v_med3_f32 v64, v64, s93, v223
	v_add_f32_e32 v68, 1.0, v68
	v_rcp_f32_e32 v68, v68
	s_nop 0
	v_mul_f32_e32 v65, v68, v65
	v_mul_f32_e32 v68, v77, v0
	v_mul_f32_e32 v65, v68, v65
	v_mul_f32_e32 v68, 0xbfb8aa3b, v66
	v_exp_f32_e32 v68, v68
	v_mul_f32_e32 v65, 0x41800000, v65
	v_med3_f32 v65, v65, s93, v223
	v_add_f32_e32 v68, 1.0, v68
	v_rcp_f32_e32 v68, v68
	s_nop 0
	v_mul_f32_e32 v66, v68, v66
	v_mul_f32_e32 v68, v78, v0
	v_mul_f32_e32 v66, v68, v66
	v_mul_f32_e32 v68, 0xbfb8aa3b, v67
	v_exp_f32_e32 v68, v68
	v_mul_f32_e32 v66, 0x41800000, v66
	v_add_f32_e32 v68, 1.0, v68
	v_rcp_f32_e32 v68, v68
	s_nop 0
	v_mul_f32_e32 v67, v68, v67
	v_mul_f32_e32 v68, v79, v0
	v_mul_f32_e32 v67, v68, v67
	v_mov_b32_e32 v215, v1
	v_cvt_pk_fp8_f32 v215, v64, v65
	v_mul_f32_e32 v67, 0x41800000, v67
	v_med3_f32 v64, v66, s93, v223
	v_med3_f32 v65, v67, s93, v223
	v_cvt_pk_fp8_f32 v215, v64, v65 op_sel:[0,0,1]
	v_and_b32_e32 v242, 32, v179
	v_lshrrev_b32_e32 v242, 3, v242
	v_lshl_add_u32 v242, v242, 1, v242
	v_mov_b32_e32 v243, 0
	v_lshl_add_u64 v[216:217], v[4:5], 0, v[242:243]
	s_nop 1
	v_permlane32_swap_b32_e32 v212, v213
	v_permlane32_swap_b32_e32 v214, v215
	global_store_dwordx4 v[216:217], v[212:215], off
	s_waitcnt vmcnt(12)
	v_lshlrev_b32_e32 v64, 16, v90
	v_mul_f32_e32 v68, 0xbfb8aa3b, v64
	v_exp_f32_e32 v68, v68
	v_and_b32_e32 v65, 0xffff0000, v90
	v_mul_f32_e32 v48, v48, v0
	v_lshlrev_b32_e32 v66, 16, v91
	v_add_f32_e32 v68, 1.0, v68
	v_rcp_f32_e32 v68, v68
	v_mul_f32_e32 v49, v49, v0
	v_and_b32_e32 v67, 0xffff0000, v91
	v_mul_f32_e32 v50, v50, v0
	v_mul_f32_e32 v64, v68, v64
	v_mul_f32_e32 v48, v48, v64
	v_mul_f32_e32 v64, 0xbfb8aa3b, v65
	v_exp_f32_e32 v64, v64
	v_mul_f32_e32 v51, v51, v0
	v_mul_f32_e32 v48, 0x41800000, v48
	v_med3_f32 v48, v48, s93, v223
	v_add_f32_e32 v64, 1.0, v64
	v_rcp_f32_e32 v64, v64
	s_nop 0
	v_mul_f32_e32 v64, v64, v65
	v_mul_f32_e32 v49, v49, v64
	v_mul_f32_e32 v64, 0xbfb8aa3b, v66
	v_exp_f32_e32 v64, v64
	v_mul_f32_e32 v49, 0x41800000, v49
	v_med3_f32 v49, v49, s93, v223
	v_add_f32_e32 v64, 1.0, v64
	v_rcp_f32_e32 v64, v64
	s_nop 0
	v_mul_f32_e32 v64, v64, v66
	v_mul_f32_e32 v50, v50, v64
	v_mul_f32_e32 v64, 0xbfb8aa3b, v67
	v_exp_f32_e32 v64, v64
	v_mul_f32_e32 v50, 0x41800000, v50
	v_add_f32_e32 v64, 1.0, v64
	v_rcp_f32_e32 v64, v64
	s_nop 0
	v_mul_f32_e32 v64, v64, v67
	v_mul_f32_e32 v51, v51, v64
	v_mov_b32_e32 v212, v1
	v_cvt_pk_fp8_f32 v212, v48, v49
	v_mul_f32_e32 v51, 0x41800000, v51
	v_med3_f32 v48, v50, s93, v223
	v_med3_f32 v49, v51, s93, v223
	v_cvt_pk_fp8_f32 v212, v48, v49 op_sel:[0,0,1]
	s_waitcnt vmcnt(11)
	v_lshlrev_b32_e32 v48, 16, v88
	v_mul_f32_e32 v64, 0xbfb8aa3b, v48
	v_exp_f32_e32 v64, v64
	v_and_b32_e32 v49, 0xffff0000, v88
	v_mul_f32_e32 v52, v52, v0
	v_lshlrev_b32_e32 v50, 16, v89
	v_add_f32_e32 v64, 1.0, v64
	v_rcp_f32_e32 v64, v64
	v_and_b32_e32 v51, 0xffff0000, v89
	v_mul_f32_e32 v48, v64, v48
	v_mul_f32_e32 v48, v52, v48
	v_mul_f32_e32 v52, 0xbfb8aa3b, v49
	v_exp_f32_e32 v52, v52
	v_mul_f32_e32 v48, 0x41800000, v48
	v_med3_f32 v48, v48, s93, v223
	v_add_f32_e32 v52, 1.0, v52
	v_rcp_f32_e32 v52, v52
	s_nop 0
	v_mul_f32_e32 v49, v52, v49
	v_mul_f32_e32 v52, v53, v0
	v_mul_f32_e32 v49, v52, v49
	v_mul_f32_e32 v52, 0xbfb8aa3b, v50
	v_exp_f32_e32 v52, v52
	v_mul_f32_e32 v49, 0x41800000, v49
	v_med3_f32 v49, v49, s93, v223
	v_add_f32_e32 v52, 1.0, v52
	v_rcp_f32_e32 v52, v52
	s_nop 0
	v_mul_f32_e32 v50, v52, v50
	v_mul_f32_e32 v52, v54, v0
	v_mul_f32_e32 v50, v52, v50
	v_mul_f32_e32 v52, 0xbfb8aa3b, v51
	v_exp_f32_e32 v52, v52
	v_mul_f32_e32 v50, 0x41800000, v50
	v_add_f32_e32 v52, 1.0, v52
	v_rcp_f32_e32 v52, v52
	s_nop 0
	v_mul_f32_e32 v51, v52, v51
	v_mul_f32_e32 v52, v55, v0
	v_mul_f32_e32 v51, v52, v51
	v_mov_b32_e32 v214, v1
	v_cvt_pk_fp8_f32 v214, v48, v49
	v_mul_f32_e32 v51, 0x41800000, v51
	v_med3_f32 v48, v50, s93, v223
	v_med3_f32 v49, v51, s93, v223
	v_cvt_pk_fp8_f32 v214, v48, v49 op_sel:[0,0,1]
	s_waitcnt vmcnt(10)
	v_lshlrev_b32_e32 v48, 16, v86
	v_mul_f32_e32 v52, 0xbfb8aa3b, v48
	v_exp_f32_e32 v52, v52
	v_and_b32_e32 v49, 0xffff0000, v86
	v_lshlrev_b32_e32 v50, 16, v87
	v_and_b32_e32 v51, 0xffff0000, v87
	v_add_f32_e32 v52, 1.0, v52
	v_rcp_f32_e32 v52, v52
	s_nop 0
	v_mul_f32_e32 v48, v52, v48
	v_mul_f32_e32 v52, v56, v0
	v_mul_f32_e32 v48, v52, v48
	v_mul_f32_e32 v52, 0xbfb8aa3b, v49
	v_exp_f32_e32 v52, v52
	v_mul_f32_e32 v48, 0x41800000, v48
	v_med3_f32 v48, v48, s93, v223
	v_add_f32_e32 v52, 1.0, v52
	v_rcp_f32_e32 v52, v52
	s_nop 0
	v_mul_f32_e32 v49, v52, v49
	v_mul_f32_e32 v52, v57, v0
	v_mul_f32_e32 v49, v52, v49
	v_mul_f32_e32 v52, 0xbfb8aa3b, v50
	v_exp_f32_e32 v52, v52
	v_mul_f32_e32 v49, 0x41800000, v49
	v_med3_f32 v49, v49, s93, v223
	v_add_f32_e32 v52, 1.0, v52
	v_rcp_f32_e32 v52, v52
	s_nop 0
	v_mul_f32_e32 v50, v52, v50
	v_mul_f32_e32 v52, v58, v0
	v_mul_f32_e32 v50, v52, v50
	v_mul_f32_e32 v52, 0xbfb8aa3b, v51
	v_exp_f32_e32 v52, v52
	v_mul_f32_e32 v50, 0x41800000, v50
	v_add_f32_e32 v52, 1.0, v52
	v_rcp_f32_e32 v52, v52
	s_nop 0
	v_mul_f32_e32 v51, v52, v51
	v_mul_f32_e32 v52, v59, v0
	v_mul_f32_e32 v51, v52, v51
	v_mov_b32_e32 v213, v1
	v_cvt_pk_fp8_f32 v213, v48, v49
	v_mul_f32_e32 v51, 0x41800000, v51
	v_med3_f32 v48, v50, s93, v223
	v_med3_f32 v49, v51, s93, v223
	v_cvt_pk_fp8_f32 v213, v48, v49 op_sel:[0,0,1]
	s_waitcnt vmcnt(9)
; DI float bf2f(unsigned b) { return __uint_as_float(b << 16); }
; template <int DQK, int W1, int DV, int VW, int MODE> ...
;     ...
; #pragma unroll
;   for (int cb = 0; cb < NCB; ++cb)
; #pragma unroll
;     for (int g = 0; g < 4; ++g) {
;       const int dv = 32 * cb + 8 * g + 4 * hi;
;       const u32x2 gg = ggv[cb * 4 + g];
;       float gv[4] = {bf2f(gg[0] & 0xffffu), bf2f(gg[0] >> 16), bf2f(gg[1] & 0xffffu), bf2f(gg[1] >> 16)};
;       float ov[4];
; #pragma unroll
;       for (int j = 0; j < 4; ++j) {
;         const float sg = gv[j] * __builtin_amdgcn_rcpf(1.f + __builtin_amdgcn_exp2f(-LOG2E * gv[j]));
;         ov[j] = o[cb][4 * g + j] * inv * sg;
;       }
;       *(unsigned*)((unsigned char*)yrow + dv) = pk4_fp8(ov[0] * Y_SCALE, ov[1] * Y_SCALE, ov[2] * Y_SCALE, ov[3] * Y_SCALE);
;       __builtin_amdgcn_sched_barrier(0);
;     }
	v_lshlrev_b32_e32 v48, 16, v84
	v_mul_f32_e32 v52, 0xbfb8aa3b, v48
	v_exp_f32_e32 v52, v52
	v_and_b32_e32 v49, 0xffff0000, v84
	v_lshlrev_b32_e32 v50, 16, v85
	v_and_b32_e32 v51, 0xffff0000, v85
	v_add_f32_e32 v52, 1.0, v52
	v_rcp_f32_e32 v52, v52
	s_nop 0
	v_mul_f32_e32 v48, v52, v48
	v_mul_f32_e32 v52, v60, v0
	v_mul_f32_e32 v48, v52, v48
	v_mul_f32_e32 v52, 0xbfb8aa3b, v49
	v_exp_f32_e32 v52, v52
	v_mul_f32_e32 v48, 0x41800000, v48
	v_med3_f32 v48, v48, s93, v223
	v_add_f32_e32 v52, 1.0, v52
	v_rcp_f32_e32 v52, v52
	s_nop 0
	v_mul_f32_e32 v49, v52, v49
	v_mul_f32_e32 v52, v61, v0
	v_mul_f32_e32 v49, v52, v49
	v_mul_f32_e32 v52, 0xbfb8aa3b, v50
	v_exp_f32_e32 v52, v52
	v_mul_f32_e32 v49, 0x41800000, v49
	v_med3_f32 v49, v49, s93, v223
	v_add_f32_e32 v52, 1.0, v52
	v_rcp_f32_e32 v52, v52
	s_nop 0
	v_mul_f32_e32 v50, v52, v50
	v_mul_f32_e32 v52, v62, v0
	v_mul_f32_e32 v50, v52, v50
	v_mul_f32_e32 v52, 0xbfb8aa3b, v51
	v_exp_f32_e32 v52, v52
	v_mul_f32_e32 v50, 0x41800000, v50
	v_add_f32_e32 v52, 1.0, v52
	v_rcp_f32_e32 v52, v52
	s_nop 0
	v_mul_f32_e32 v51, v52, v51
	v_mul_f32_e32 v52, v63, v0
	v_mul_f32_e32 v51, v52, v51
	v_mov_b32_e32 v215, v1
	v_cvt_pk_fp8_f32 v215, v48, v49
	v_mul_f32_e32 v51, 0x41800000, v51
	v_med3_f32 v48, v50, s93, v223
	v_med3_f32 v49, v51, s93, v223
	v_cvt_pk_fp8_f32 v215, v48, v49 op_sel:[0,0,1]
	s_nop 1
	v_permlane32_swap_b32_e32 v212, v213
	v_permlane32_swap_b32_e32 v214, v215
	global_store_dwordx4 v[216:217], v[212:215], off offset:32
	s_waitcnt vmcnt(9)
	v_lshlrev_b32_e32 v48, 16, v82
	v_mul_f32_e32 v52, 0xbfb8aa3b, v48
	v_exp_f32_e32 v52, v52
	v_and_b32_e32 v49, 0xffff0000, v82
	v_mul_f32_e32 v32, v32, v0
	v_lshlrev_b32_e32 v50, 16, v83
	v_add_f32_e32 v52, 1.0, v52
	v_rcp_f32_e32 v52, v52
	v_mul_f32_e32 v33, v33, v0
	v_and_b32_e32 v51, 0xffff0000, v83
	v_mul_f32_e32 v34, v34, v0
	v_mul_f32_e32 v48, v52, v48
	v_mul_f32_e32 v32, v32, v48
	v_mul_f32_e32 v48, 0xbfb8aa3b, v49
	v_exp_f32_e32 v48, v48
	v_mul_f32_e32 v35, v35, v0
	v_mul_f32_e32 v32, 0x41800000, v32
	v_med3_f32 v32, v32, s93, v223
	v_add_f32_e32 v48, 1.0, v48
	v_rcp_f32_e32 v48, v48
	s_nop 0
	v_mul_f32_e32 v48, v48, v49
	v_mul_f32_e32 v33, v33, v48
	v_mul_f32_e32 v48, 0xbfb8aa3b, v50
	v_exp_f32_e32 v48, v48
	v_mul_f32_e32 v33, 0x41800000, v33
	v_med3_f32 v33, v33, s93, v223
	v_add_f32_e32 v48, 1.0, v48
	v_rcp_f32_e32 v48, v48
	s_nop 0
	v_mul_f32_e32 v48, v48, v50
	v_mul_f32_e32 v34, v34, v48
	v_mul_f32_e32 v48, 0xbfb8aa3b, v51
	v_exp_f32_e32 v48, v48
	v_mul_f32_e32 v34, 0x41800000, v34
	v_add_f32_e32 v48, 1.0, v48
	v_rcp_f32_e32 v48, v48
	s_nop 0
	v_mul_f32_e32 v48, v48, v51
	v_mul_f32_e32 v35, v35, v48
	v_mov_b32_e32 v212, v1
	v_cvt_pk_fp8_f32 v212, v32, v33
	v_mul_f32_e32 v35, 0x41800000, v35
	v_med3_f32 v32, v34, s93, v223
	v_med3_f32 v33, v35, s93, v223
	v_cvt_pk_fp8_f32 v212, v32, v33 op_sel:[0,0,1]
	s_waitcnt vmcnt(8)
	v_lshlrev_b32_e32 v32, 16, v80
	v_mul_f32_e32 v48, 0xbfb8aa3b, v32
	v_exp_f32_e32 v48, v48
	v_and_b32_e32 v33, 0xffff0000, v80
	v_mul_f32_e32 v36, v36, v0
	v_lshlrev_b32_e32 v34, 16, v81
	v_add_f32_e32 v48, 1.0, v48
	v_rcp_f32_e32 v48, v48
	v_and_b32_e32 v35, 0xffff0000, v81
	v_mul_f32_e32 v32, v48, v32
	v_mul_f32_e32 v32, v36, v32
	v_mul_f32_e32 v36, 0xbfb8aa3b, v33
	v_exp_f32_e32 v36, v36
	v_mul_f32_e32 v32, 0x41800000, v32
	v_med3_f32 v32, v32, s93, v223
	v_add_f32_e32 v36, 1.0, v36
	v_rcp_f32_e32 v36, v36
	s_nop 0
	v_mul_f32_e32 v33, v36, v33
	v_mul_f32_e32 v36, v37, v0
	v_mul_f32_e32 v33, v36, v33
	v_mul_f32_e32 v36, 0xbfb8aa3b, v34
	v_exp_f32_e32 v36, v36
	v_mul_f32_e32 v33, 0x41800000, v33
	v_med3_f32 v33, v33, s93, v223
	v_add_f32_e32 v36, 1.0, v36
	v_rcp_f32_e32 v36, v36
	s_nop 0
	v_mul_f32_e32 v34, v36, v34
	v_mul_f32_e32 v36, v38, v0
	v_mul_f32_e32 v34, v36, v34
	v_mul_f32_e32 v36, 0xbfb8aa3b, v35
	v_exp_f32_e32 v36, v36
	v_mul_f32_e32 v34, 0x41800000, v34
	v_add_f32_e32 v36, 1.0, v36
	v_rcp_f32_e32 v36, v36
	s_nop 0
	v_mul_f32_e32 v35, v36, v35
	v_mul_f32_e32 v36, v39, v0
	v_mul_f32_e32 v35, v36, v35
	v_mov_b32_e32 v214, v1
	v_cvt_pk_fp8_f32 v214, v32, v33
	v_mul_f32_e32 v35, 0x41800000, v35
	v_med3_f32 v32, v34, s93, v223
	v_med3_f32 v33, v35, s93, v223
	v_cvt_pk_fp8_f32 v214, v32, v33 op_sel:[0,0,1]
	s_waitcnt vmcnt(7)
	v_lshlrev_b32_e32 v32, 16, v14
	v_mul_f32_e32 v34, 0xbfb8aa3b, v32
	v_exp_f32_e32 v34, v34
	v_and_b32_e32 v14, 0xffff0000, v14
	v_lshlrev_b32_e32 v33, 16, v15
	v_and_b32_e32 v15, 0xffff0000, v15
	v_add_f32_e32 v34, 1.0, v34
	v_rcp_f32_e32 v34, v34
	s_nop 0
	v_mul_f32_e32 v32, v34, v32
	v_mul_f32_e32 v34, v40, v0
	v_mul_f32_e32 v32, v34, v32
	v_mul_f32_e32 v34, 0xbfb8aa3b, v14
	v_exp_f32_e32 v34, v34
	v_mul_f32_e32 v32, 0x41800000, v32
	v_med3_f32 v32, v32, s93, v223
	v_add_f32_e32 v34, 1.0, v34
	v_rcp_f32_e32 v34, v34
	s_nop 0
	v_mul_f32_e32 v14, v34, v14
	v_mul_f32_e32 v34, v41, v0
	v_mul_f32_e32 v14, v34, v14
	v_mul_f32_e32 v34, 0xbfb8aa3b, v33
	v_exp_f32_e32 v34, v34
	v_mul_f32_e32 v14, 0x41800000, v14
	v_med3_f32 v14, v14, s93, v223
	v_add_f32_e32 v34, 1.0, v34
	v_rcp_f32_e32 v34, v34
	s_nop 0
	v_mul_f32_e32 v33, v34, v33
	v_mul_f32_e32 v34, v42, v0
	v_mul_f32_e32 v33, v34, v33
	v_mul_f32_e32 v34, 0xbfb8aa3b, v15
	v_exp_f32_e32 v34, v34
	v_mul_f32_e32 v33, 0x41800000, v33
	v_add_f32_e32 v34, 1.0, v34
	v_rcp_f32_e32 v34, v34
	s_nop 0
	v_mul_f32_e32 v15, v34, v15
	v_mul_f32_e32 v34, v43, v0
	v_mul_f32_e32 v15, v34, v15
	v_mov_b32_e32 v213, v1
	v_cvt_pk_fp8_f32 v213, v32, v14
	v_mul_f32_e32 v15, 0x41800000, v15
	v_med3_f32 v14, v33, s93, v223
	v_med3_f32 v15, v15, s93, v223
	v_cvt_pk_fp8_f32 v213, v14, v15 op_sel:[0,0,1]
	s_waitcnt vmcnt(6)
; DI float bf2f(unsigned b) { return __uint_as_float(b << 16); }
; template <int DQK, int W1, int DV, int VW, int MODE> ...
;     ...
; #pragma unroll
;   for (int cb = 0; cb < NCB; ++cb)
; #pragma unroll
;     for (int g = 0; g < 4; ++g) {
;       const int dv = 32 * cb + 8 * g + 4 * hi;
;       const u32x2 gg = ggv[cb * 4 + g];
;       float gv[4] = {bf2f(gg[0] & 0xffffu), bf2f(gg[0] >> 16), bf2f(gg[1] & 0xffffu), bf2f(gg[1] >> 16)};
;       float ov[4];
; #pragma unroll
;       for (int j = 0; j < 4; ++j) {
;         const float sg = gv[j] * __builtin_amdgcn_rcpf(1.f + __builtin_amdgcn_exp2f(-LOG2E * gv[j]));
;         ov[j] = o[cb][4 * g + j] * inv * sg;
;       }
;       *(unsigned*)((unsigned char*)yrow + dv) = pk4_fp8(ov[0] * Y_SCALE, ov[1] * Y_SCALE, ov[2] * Y_SCALE, ov[3] * Y_SCALE);
;       __builtin_amdgcn_sched_barrier(0);
;     }
	v_lshlrev_b32_e32 v14, 16, v12
	v_mul_f32_e32 v32, 0xbfb8aa3b, v14
	v_exp_f32_e32 v32, v32
	v_and_b32_e32 v12, 0xffff0000, v12
	v_lshlrev_b32_e32 v15, 16, v13
	v_and_b32_e32 v13, 0xffff0000, v13
	v_add_f32_e32 v32, 1.0, v32
	v_rcp_f32_e32 v32, v32
	s_nop 0
	v_mul_f32_e32 v14, v32, v14
	v_mul_f32_e32 v32, v44, v0
	v_mul_f32_e32 v14, v32, v14
	v_mul_f32_e32 v32, 0xbfb8aa3b, v12
	v_exp_f32_e32 v32, v32
	v_mul_f32_e32 v14, 0x41800000, v14
	v_med3_f32 v14, v14, s93, v223
	v_add_f32_e32 v32, 1.0, v32
	v_rcp_f32_e32 v32, v32
	s_nop 0
	v_mul_f32_e32 v12, v32, v12
	v_mul_f32_e32 v32, v45, v0
	v_mul_f32_e32 v12, v32, v12
	v_mul_f32_e32 v32, 0xbfb8aa3b, v15
	v_exp_f32_e32 v32, v32
	v_mul_f32_e32 v12, 0x41800000, v12
	v_med3_f32 v12, v12, s93, v223
	v_add_f32_e32 v32, 1.0, v32
	v_rcp_f32_e32 v32, v32
	s_nop 0
	v_mul_f32_e32 v15, v32, v15
	v_mul_f32_e32 v32, v46, v0
	v_mul_f32_e32 v15, v32, v15
	v_mul_f32_e32 v32, 0xbfb8aa3b, v13
	v_exp_f32_e32 v32, v32
	v_mul_f32_e32 v15, 0x41800000, v15
	v_add_f32_e32 v32, 1.0, v32
	v_rcp_f32_e32 v32, v32
	s_nop 0
	v_mul_f32_e32 v13, v32, v13
	v_mul_f32_e32 v32, v47, v0
	v_mul_f32_e32 v13, v32, v13
	v_mov_b32_e32 v215, v1
	v_cvt_pk_fp8_f32 v215, v14, v12
	v_mul_f32_e32 v13, 0x41800000, v13
	v_med3_f32 v12, v15, s93, v223
	v_med3_f32 v13, v13, s93, v223
	v_cvt_pk_fp8_f32 v215, v12, v13 op_sel:[0,0,1]
	s_nop 1
	v_permlane32_swap_b32_e32 v212, v213
	v_permlane32_swap_b32_e32 v214, v215
	global_store_dwordx4 v[216:217], v[212:215], off offset:64
	s_waitcnt vmcnt(6)
	v_lshlrev_b32_e32 v12, 16, v10
	v_mul_f32_e32 v14, 0xbfb8aa3b, v12
	v_exp_f32_e32 v14, v14
	v_and_b32_e32 v10, 0xffff0000, v10
	v_lshlrev_b32_e32 v13, 16, v11
	v_and_b32_e32 v11, 0xffff0000, v11
	v_add_f32_e32 v14, 1.0, v14
	v_rcp_f32_e32 v14, v14
	s_nop 0
	v_mul_f32_e32 v12, v14, v12
	v_mul_f32_e32 v14, v16, v0
	v_mul_f32_e32 v12, v14, v12
	v_mul_f32_e32 v14, 0xbfb8aa3b, v10
	v_exp_f32_e32 v14, v14
	v_mul_f32_e32 v12, 0x41800000, v12
	v_med3_f32 v12, v12, s93, v223
	v_add_f32_e32 v14, 1.0, v14
	v_rcp_f32_e32 v14, v14
	s_nop 0
	v_mul_f32_e32 v10, v14, v10
	v_mul_f32_e32 v14, v17, v0
	v_mul_f32_e32 v10, v14, v10
	v_mul_f32_e32 v14, 0xbfb8aa3b, v13
	v_exp_f32_e32 v14, v14
	v_mul_f32_e32 v10, 0x41800000, v10
	v_med3_f32 v10, v10, s93, v223
	v_add_f32_e32 v14, 1.0, v14
	v_rcp_f32_e32 v14, v14
	s_nop 0
	v_mul_f32_e32 v13, v14, v13
	v_mul_f32_e32 v14, v18, v0
	v_mul_f32_e32 v13, v14, v13
	v_mul_f32_e32 v14, 0xbfb8aa3b, v11
	v_exp_f32_e32 v14, v14
	v_mul_f32_e32 v13, 0x41800000, v13
	v_add_f32_e32 v14, 1.0, v14
	v_rcp_f32_e32 v14, v14
	s_nop 0
	v_mul_f32_e32 v11, v14, v11
	v_mul_f32_e32 v14, v19, v0
	v_mul_f32_e32 v11, v14, v11
	v_mov_b32_e32 v212, v1
	v_cvt_pk_fp8_f32 v212, v12, v10
	v_mul_f32_e32 v11, 0x41800000, v11
	v_med3_f32 v10, v13, s93, v223
	v_med3_f32 v11, v11, s93, v223
	v_cvt_pk_fp8_f32 v212, v10, v11 op_sel:[0,0,1]
	s_waitcnt vmcnt(5)
	v_lshlrev_b32_e32 v10, 16, v8
	v_mul_f32_e32 v12, 0xbfb8aa3b, v10
	v_exp_f32_e32 v12, v12
	v_and_b32_e32 v8, 0xffff0000, v8
	v_lshlrev_b32_e32 v11, 16, v9
	v_and_b32_e32 v9, 0xffff0000, v9
	v_add_f32_e32 v12, 1.0, v12
	v_rcp_f32_e32 v12, v12
	s_nop 0
	v_mul_f32_e32 v10, v12, v10
	v_mul_f32_e32 v12, v20, v0
	v_mul_f32_e32 v10, v12, v10
	v_mul_f32_e32 v12, 0xbfb8aa3b, v8
	v_exp_f32_e32 v12, v12
	v_mul_f32_e32 v10, 0x41800000, v10
	v_med3_f32 v10, v10, s93, v223
	v_add_f32_e32 v12, 1.0, v12
	v_rcp_f32_e32 v12, v12
	s_nop 0
	v_mul_f32_e32 v8, v12, v8
	v_mul_f32_e32 v12, v21, v0
	v_mul_f32_e32 v8, v12, v8
	v_mul_f32_e32 v12, 0xbfb8aa3b, v11
	v_exp_f32_e32 v12, v12
	v_mul_f32_e32 v8, 0x41800000, v8
	v_med3_f32 v8, v8, s93, v223
	v_add_f32_e32 v12, 1.0, v12
	v_rcp_f32_e32 v12, v12
	s_nop 0
	v_mul_f32_e32 v11, v12, v11
	v_mul_f32_e32 v12, v22, v0
	v_mul_f32_e32 v11, v12, v11
	v_mul_f32_e32 v12, 0xbfb8aa3b, v9
	v_exp_f32_e32 v12, v12
	v_mul_f32_e32 v11, 0x41800000, v11
	v_add_f32_e32 v12, 1.0, v12
	v_rcp_f32_e32 v12, v12
	s_nop 0
	v_mul_f32_e32 v9, v12, v9
	v_mul_f32_e32 v12, v23, v0
	v_mul_f32_e32 v9, v12, v9
	v_mov_b32_e32 v214, v1
	v_cvt_pk_fp8_f32 v214, v10, v8
	v_mul_f32_e32 v9, 0x41800000, v9
	v_med3_f32 v8, v11, s93, v223
	v_med3_f32 v9, v9, s93, v223
	v_cvt_pk_fp8_f32 v214, v8, v9 op_sel:[0,0,1]
	s_waitcnt vmcnt(4)
	v_lshlrev_b32_e32 v8, 16, v6
	v_mul_f32_e32 v10, 0xbfb8aa3b, v8
	v_exp_f32_e32 v10, v10
	v_and_b32_e32 v6, 0xffff0000, v6
	v_lshlrev_b32_e32 v9, 16, v7
	v_and_b32_e32 v7, 0xffff0000, v7
	v_add_f32_e32 v10, 1.0, v10
	v_rcp_f32_e32 v10, v10
	s_nop 0
	v_mul_f32_e32 v8, v10, v8
	v_mul_f32_e32 v10, v24, v0
	v_mul_f32_e32 v8, v10, v8
	v_mul_f32_e32 v10, 0xbfb8aa3b, v6
	v_exp_f32_e32 v10, v10
	v_mul_f32_e32 v8, 0x41800000, v8
	v_med3_f32 v8, v8, s93, v223
	v_add_f32_e32 v10, 1.0, v10
	v_rcp_f32_e32 v10, v10
	s_nop 0
	v_mul_f32_e32 v6, v10, v6
	v_mul_f32_e32 v10, v25, v0
	v_mul_f32_e32 v6, v10, v6
	v_mul_f32_e32 v10, 0xbfb8aa3b, v9
	v_exp_f32_e32 v10, v10
	v_mul_f32_e32 v6, 0x41800000, v6
	v_med3_f32 v6, v6, s93, v223
	v_add_f32_e32 v10, 1.0, v10
	v_rcp_f32_e32 v10, v10
	s_nop 0
	v_mul_f32_e32 v9, v10, v9
	v_mul_f32_e32 v10, v26, v0
	v_mul_f32_e32 v9, v10, v9
	v_mul_f32_e32 v10, 0xbfb8aa3b, v7
	v_exp_f32_e32 v10, v10
	v_mul_f32_e32 v9, 0x41800000, v9
	v_add_f32_e32 v10, 1.0, v10
	v_rcp_f32_e32 v10, v10
	s_nop 0
	v_mul_f32_e32 v7, v10, v7
	v_mul_f32_e32 v10, v27, v0
	v_mul_f32_e32 v7, v10, v7
	v_mov_b32_e32 v213, v1
	v_cvt_pk_fp8_f32 v213, v8, v6
	v_mul_f32_e32 v7, 0x41800000, v7
	v_med3_f32 v6, v9, s93, v223
	v_med3_f32 v7, v7, s93, v223
	v_cvt_pk_fp8_f32 v213, v6, v7 op_sel:[0,0,1]
	s_waitcnt vmcnt(3)
	v_lshlrev_b32_e32 v6, 16, v2
	v_mul_f32_e32 v8, 0xbfb8aa3b, v6
	v_exp_f32_e32 v8, v8
	v_and_b32_e32 v2, 0xffff0000, v2
	v_lshlrev_b32_e32 v7, 16, v3
	v_and_b32_e32 v3, 0xffff0000, v3
	v_add_f32_e32 v8, 1.0, v8
	v_rcp_f32_e32 v8, v8
	s_nop 0
	v_mul_f32_e32 v6, v8, v6
	v_mul_f32_e32 v8, v28, v0
	v_mul_f32_e32 v6, v8, v6
	v_mul_f32_e32 v8, 0xbfb8aa3b, v2
	v_exp_f32_e32 v8, v8
	s_nop 0
	v_add_f32_e32 v8, 1.0, v8
	v_rcp_f32_e32 v8, v8
	s_nop 0
	v_mul_f32_e32 v2, v8, v2
	v_mul_f32_e32 v8, v29, v0
	v_mul_f32_e32 v2, v8, v2
	v_mul_f32_e32 v8, 0xbfb8aa3b, v7
	v_exp_f32_e32 v8, v8
	v_mul_f32_e32 v2, 0x41800000, v2
	v_med3_f32 v2, v2, s93, v223
	v_add_f32_e32 v8, 1.0, v8
	v_rcp_f32_e32 v8, v8
	s_nop 0
	v_mul_f32_e32 v7, v8, v7
	v_mul_f32_e32 v8, v30, v0
	v_mul_f32_e32 v7, v8, v7
	v_mul_f32_e32 v8, 0xbfb8aa3b, v3
	v_exp_f32_e32 v8, v8
	v_mul_f32_e32 v0, v31, v0
	v_add_f32_e32 v8, 1.0, v8
	v_rcp_f32_e32 v8, v8
	s_nop 0
	v_mul_f32_e32 v3, v8, v3
	v_mul_f32_e32 v0, v0, v3
	v_mul_f32_e32 v3, 0x41800000, v6
	v_mul_f32_e32 v6, 0x41800000, v7
	v_med3_f32 v3, v3, s93, v223
	v_mov_b32_e32 v215, v1
	v_cvt_pk_fp8_f32 v215, v3, v2
	v_mul_f32_e32 v0, 0x41800000, v0
	v_med3_f32 v2, v6, s93, v223
	v_med3_f32 v0, v0, s93, v223
	v_cvt_pk_fp8_f32 v215, v2, v0 op_sel:[0,0,1]
	s_nop 1
	v_permlane32_swap_b32_e32 v212, v213
	v_permlane32_swap_b32_e32 v214, v215
	global_store_dwordx4 v[216:217], v[212:215], off offset:96

; template <int DQK, int W1, int DV, int VW, int MODE> ...
;     ...
;         f32x16 e0 = s[0], e1 = s[1];
;         if (MODE != 0) { const float nm = -m; e0 = e0 + nm; e1 = e1 + nm; }
; #pragma unroll
;         for (int i = 0; i < 16; ++i) { e0[i] = __builtin_amdgcn_exp2f(e0[i]); e1[i] = __builtin_amdgcn_exp2f(e1[i]); }
;         s[0] = e0; s[1] = e1;
;         const f32x16 sm = e0 + e1;
;         typedef __attribute__((ext_vector_type(8))) float f32x8;
;         const f32x8 h8 = sm.lo + sm.hi;
;         const f32x4 h4 = h8.lo + h8.hi;
;         const f32x2 h2 = h4.lo + h4.hi;
;         l += h2[0] + h2[1];
;       }
;       bf16x8 pb[2][2];
; #pragma unroll
;       for (int n = 0; n < 2; ++n)
; #pragma unroll
;         for (int s2 = 0; s2 < 2; ++s2) {
;           u32x4 pw = {pk2(s[n][8 * s2 + 0], s[n][8 * s2 + 1]), pk2(s[n][8 * s2 + 2], s[n][8 * s2 + 3]),
;                       pk2(s[n][8 * s2 + 4], s[n][8 * s2 + 5]), pk2(s[n][8 * s2 + 6], s[n][8 * s2 + 7])};
;           pb[n][s2] = __builtin_bit_cast(bf16x8, pw);
;         }
;       pv_block<0>(o[0], bufa + vlane, pb);
;       if constexpr (NCB > 1) pv_block<1>(o[1], bufa + vlane, pb);
;       if constexpr (NCB > 2) pv_block<2>(o[2], bufa + vlane, pb);
;       if constexpr (NCB > 3) pv_block<3>(o[3], bufa + vlane, pb);
;     }
;     asm volatile("s_waitcnt vmcnt(0)" ::: "memory");
;     __syncthreads();
.LBB0_1291:
	v_pk_add_f32 v[96:97], v[108:109], v[94:95] op_sel_hi:[1,0]
	v_pk_add_f32 v[98:99], v[106:107], v[94:95] op_sel_hi:[1,0]
	v_pk_add_f32 v[100:101], v[104:105], v[94:95] op_sel_hi:[1,0]
	v_pk_add_f32 v[102:103], v[102:103], v[94:95] op_sel_hi:[1,0]
	v_pk_add_f32 v[72:73], v[72:73], v[94:95] op_sel_hi:[1,0]
	v_pk_add_f32 v[70:71], v[70:71], v[94:95] op_sel_hi:[1,0]
	v_pk_add_f32 v[68:69], v[68:69], v[94:95] op_sel_hi:[1,0]
	v_mov_b32_e32 v95, v94
	v_mov_b64_e32 v[74:75], s[82:83]
	v_pk_add_f32 v[66:67], v[66:67], v[94:95]
	v_pk_add_f32 v[92:93], v[92:93], v[94:95] op_sel_hi:[1,0]
	v_pk_add_f32 v[90:91], v[90:91], v[94:95] op_sel_hi:[1,0]
	v_pk_add_f32 v[86:87], v[86:87], v[94:95] op_sel_hi:[1,0]
	v_pk_add_f32 v[84:85], v[84:85], v[94:95] op_sel_hi:[1,0]
	v_pk_add_f32 v[82:83], v[82:83], v[94:95] op_sel_hi:[1,0]
	v_pk_add_f32 v[80:81], v[80:81], v[94:95] op_sel_hi:[1,0]
	v_pk_add_f32 v[78:79], v[78:79], v[94:95] op_sel_hi:[1,0]
	v_pk_add_f32 v[76:77], v[76:77], v[94:95]
	v_mad_u64_u32 v[74:75], s[0:1], v166, s34, v[74:75]
	v_exp_f32_e32 v66, v66
	v_exp_f32_e32 v76, v76
	v_exp_f32_e32 v67, v67
	v_exp_f32_e32 v77, v77
	v_exp_f32_e32 v68, v68
	v_exp_f32_e32 v78, v78
	v_exp_f32_e32 v69, v69
	v_exp_f32_e32 v79, v79
	v_exp_f32_e32 v70, v70
	v_exp_f32_e32 v80, v80
	v_exp_f32_e32 v71, v71
	v_exp_f32_e32 v81, v81
	v_exp_f32_e32 v72, v72
	v_exp_f32_e32 v82, v82
	v_exp_f32_e32 v73, v73
	v_exp_f32_e32 v83, v83
	v_exp_f32_e32 v94, v102
	v_exp_f32_e32 v84, v84
	v_exp_f32_e32 v95, v103
	v_exp_f32_e32 v85, v85
	v_exp_f32_e32 v100, v100
	v_exp_f32_e32 v86, v86
	v_exp_f32_e32 v101, v101
	v_exp_f32_e32 v87, v87
	v_exp_f32_e32 v98, v98
	v_exp_f32_e32 v90, v90
	v_exp_f32_e32 v99, v99
	v_exp_f32_e32 v91, v91
	v_exp_f32_e32 v96, v96
	v_exp_f32_e32 v92, v92
	v_exp_f32_e32 v97, v97
	v_exp_f32_e32 v93, v93
	v_mad_u32_u24 v75, v167, s34, v75
	v_readlane_b32 s0, v254, 7
	v_lshl_add_u64 v[74:75], v[74:75], 0, s[54:55]
	v_readlane_b32 s1, v254, 8
	s_mov_b32 s69, s55
	s_lshl_b32 s54, s54, 1
	v_lshl_add_u64 v[88:89], v[74:75], 0, s[0:1]
	v_lshl_add_u64 v[74:75], v[164:165], 0, s[68:69]
	v_lshl_add_u64 v[74:75], v[74:75], 0, s[54:55]
	s_lshl_b32 s54, s0, 1
	v_pk_add_f32 v[102:103], v[100:101], v[86:87]
	v_pk_add_f32 v[104:105], v[68:69], v[78:79]
	v_pk_add_f32 v[106:107], v[96:97], v[92:93]
	v_pk_add_f32 v[108:109], v[72:73], v[82:83]
	v_pk_add_f32 v[110:111], v[94:95], v[84:85]
	v_pk_add_f32 v[112:113], v[66:67], v[76:77]
	v_pk_add_f32 v[114:115], v[98:99], v[90:91]
	v_pk_add_f32 v[116:117], v[70:71], v[80:81]
	v_pk_add_f32 v[110:111], v[112:113], v[110:111]
	v_pk_add_f32 v[114:115], v[116:117], v[114:115]
	v_pk_add_f32 v[106:107], v[108:109], v[106:107]
	v_pk_add_f32 v[102:103], v[104:105], v[102:103]
	s_cmp_lg_u32 0, -1
	v_pk_add_f32 v[102:103], v[102:103], v[106:107]
	v_pk_add_f32 v[104:105], v[110:111], v[114:115]
	s_cselect_b32 s0, 0, 0
	v_pk_add_f32 v[102:103], v[104:105], v[102:103]
	v_cvt_pk_bf16_f32 v66, v66, v67
	v_cvt_pk_bf16_f32 v67, v68, v69
	v_cvt_pk_bf16_f32 v68, v70, v71
	v_cvt_pk_bf16_f32 v69, v72, v73
	s_add_i32 s0, s0, 0x10400
	v_add_f32_e32 v0, v102, v103
	v_cvt_pk_bf16_f32 v70, v94, v95
	v_cvt_pk_bf16_f32 v71, v100, v101
	v_cvt_pk_bf16_f32 v72, v98, v99
	v_cvt_pk_bf16_f32 v73, v96, v97
	v_cvt_pk_bf16_f32 v76, v76, v77
	v_cvt_pk_bf16_f32 v77, v78, v79
	v_cvt_pk_bf16_f32 v78, v80, v81
	v_cvt_pk_bf16_f32 v79, v82, v83
	v_cvt_pk_bf16_f32 v80, v84, v85
	v_cvt_pk_bf16_f32 v81, v86, v87
	v_cvt_pk_bf16_f32 v82, v90, v91
	v_cvt_pk_bf16_f32 v83, v92, v93
	v_add_u32_e32 v102, s0, v163
	ds_read_b64_tr_b16 v[98:99], v102 offset:0
	ds_read_b64_tr_b16 v[100:101], v102 offset:0x200
	ds_read_b64_tr_b16 v[94:95], v102 offset:0x400
	ds_read_b64_tr_b16 v[96:97], v102 offset:0x600
	ds_read_b64_tr_b16 v[90:91], v102 offset:0x800
	ds_read_b64_tr_b16 v[92:93], v102 offset:0xa00
	ds_read_b64_tr_b16 v[84:85], v102 offset:0xc00
	ds_read_b64_tr_b16 v[86:87], v102 offset:0xe00
	s_waitcnt lgkmcnt(0)
	v_add_f32_e32 v0, v193, v0
	v_mfma_f32_32x32x16_bf16 v[50:65], v[98:101], v[66:69], v[50:65]
	v_lshl_add_u64 v[74:75], v[74:75], 0, s[54:55]
	s_mov_b64 s[0:1], 0x1000
	v_readlane_b32 s28, v254, 27
	s_movk_i32 s20, 0x600
	v_readlane_b32 s3, v254, 29
	v_readlane_b32 s29, v254, 28
	v_mov_b32_e32 v163, v1
	v_mfma_f32_32x32x16_bf16 v[50:65], v[94:97], v[70:73], v[50:65]
	v_mfma_f32_32x32x16_bf16 v[50:65], v[90:93], v[76:79], v[50:65]
	v_mfma_f32_32x32x16_bf16 v[50:65], v[84:87], v[80:83], v[50:65]
	ds_read_b64_tr_b16 v[98:99], v102 offset:0x1000
	ds_read_b64_tr_b16 v[100:101], v102 offset:0x1200
	ds_read_b64_tr_b16 v[94:95], v102 offset:0x1400
	ds_read_b64_tr_b16 v[96:97], v102 offset:0x1600
	ds_read_b64_tr_b16 v[90:91], v102 offset:0x1800
	ds_read_b64_tr_b16 v[92:93], v102 offset:0x1a00
	ds_read_b64_tr_b16 v[84:85], v102 offset:0x1c00
	ds_read_b64_tr_b16 v[86:87], v102 offset:0x1e00
	s_waitcnt lgkmcnt(0)
	s_nop 0
	v_mfma_f32_32x32x16_bf16 v[34:49], v[98:101], v[66:69], v[34:49]
	v_mfma_f32_32x32x16_bf16 v[34:49], v[94:97], v[70:73], v[34:49]
	v_mfma_f32_32x32x16_bf16 v[34:49], v[90:93], v[76:79], v[34:49]
	v_mfma_f32_32x32x16_bf16 v[34:49], v[84:87], v[80:83], v[34:49]
	ds_read_b64_tr_b16 v[98:99], v102 offset:0x2000
	ds_read_b64_tr_b16 v[100:101], v102 offset:0x2200
	ds_read_b64_tr_b16 v[94:95], v102 offset:0x2400
	ds_read_b64_tr_b16 v[96:97], v102 offset:0x2600
	ds_read_b64_tr_b16 v[90:91], v102 offset:0x2800
	ds_read_b64_tr_b16 v[92:93], v102 offset:0x2a00
	ds_read_b64_tr_b16 v[84:85], v102 offset:0x2c00
	ds_read_b64_tr_b16 v[86:87], v102 offset:0x2e00
	s_waitcnt lgkmcnt(0)
	s_nop 0
	v_mfma_f32_32x32x16_bf16 v[18:33], v[98:101], v[66:69], v[18:33]
	v_mfma_f32_32x32x16_bf16 v[18:33], v[94:97], v[70:73], v[18:33]
	v_mfma_f32_32x32x16_bf16 v[18:33], v[90:93], v[76:79], v[18:33]
	v_mfma_f32_32x32x16_bf16 v[18:33], v[84:87], v[80:83], v[18:33]
	ds_read_b64_tr_b16 v[98:99], v102 offset:0x3000
	ds_read_b64_tr_b16 v[100:101], v102 offset:0x3200
	ds_read_b64_tr_b16 v[94:95], v102 offset:0x3400
	ds_read_b64_tr_b16 v[96:97], v102 offset:0x3600
	ds_read_b64_tr_b16 v[90:91], v102 offset:0x3800
	ds_read_b64_tr_b16 v[92:93], v102 offset:0x3a00
	ds_read_b64_tr_b16 v[84:85], v102 offset:0x3c00
	ds_read_b64_tr_b16 v[86:87], v102 offset:0x3e00
	s_waitcnt lgkmcnt(0)
	s_waitcnt vmcnt(0)
	s_barrier
; DI float bf2f(unsigned b) { return __uint_as_float(b << 16); }
; template <int DQK, int W1, int DV, int VW, int MODE> ...
;     ...
;   const float inv = __builtin_amdgcn_rcpf(xhalf_sum(l));
;   u32x2 ggv[NCB * 4];
; #pragma unroll
;   for (int cb = 0; cb < NCB; ++cb)
; #pragma unroll
;     for (int g = 0; g < 4; ++g) ggv[cb * 4 + g] = *(const u32x2*)(grow + 32 * cb + 8 * g + 4 * hi);
;   __builtin_amdgcn_sched_barrier(0);
; #pragma unroll
;   for (int cb = 0; cb < NCB; ++cb)
; #pragma unroll
;     for (int g = 0; g < 4; ++g) {
;       const int dv = 32 * cb + 8 * g + 4 * hi;
;       const u32x2 gg = ggv[cb * 4 + g];
;       float gv[4] = {bf2f(gg[0] & 0xffffu), bf2f(gg[0] >> 16), bf2f(gg[1] & 0xffffu), bf2f(gg[1] >> 16)};
;       float ov[4];
; #pragma unroll
;       for (int j = 0; j < 4; ++j) {
;         const float sg = gv[j] * __builtin_amdgcn_rcpf(1.f + __builtin_amdgcn_exp2f(-LOG2E * gv[j]));
;         ov[j] = o[cb][4 * g + j] * inv * sg;
;       }
;       *(unsigned*)((unsigned char*)yrow + dv) = pk4_fp8(ov[0] * Y_SCALE, ov[1] * Y_SCALE, ov[2] * Y_SCALE, ov[3] * Y_SCALE);
;       __builtin_amdgcn_sched_barrier(0);
;     }
	v_mfma_f32_32x32x16_bf16 v[2:17], v[98:101], v[66:69], v[2:17]
	v_mov_b32_e32 v66, v0
	s_nop 1
	v_permlane32_swap_b32_e32 v0, v66
	v_add_f32_e32 v102, v0, v66
	v_lshlrev_b32_e32 v0, 1, v162
	v_lshl_add_u64 v[66:67], v[74:75], 0, v[0:1]
	v_lshl_add_u64 v[98:99], v[66:67], 0, s[0:1]
	v_mfma_f32_32x32x16_bf16 v[2:17], v[94:97], v[70:73], v[2:17]
	s_movk_i32 s0, 0x1000
	v_add_co_u32_e32 v66, vcc, s0, v66
	v_rcp_f32_e32 v0, v102
	s_nop 0
	v_addc_co_u32_e32 v67, vcc, 0, v67, vcc
	v_mfma_f32_32x32x16_bf16 v[2:17], v[90:93], v[76:79], v[2:17]
	v_mfma_f32_32x32x16_bf16 v[2:17], v[84:87], v[80:83], v[2:17]
	global_load_dwordx2 v[100:101], v[66:67], off
	global_load_dwordx2 v[96:97], v[98:99], off offset:16
	global_load_dwordx2 v[94:95], v[98:99], off offset:32
	global_load_dwordx2 v[92:93], v[98:99], off offset:48
	global_load_dwordx2 v[90:91], v[98:99], off offset:64
	global_load_dwordx2 v[86:87], v[98:99], off offset:80
	global_load_dwordx2 v[84:85], v[98:99], off offset:96
	global_load_dwordx2 v[82:83], v[98:99], off offset:112
	global_load_dwordx2 v[80:81], v[98:99], off offset:128
	global_load_dwordx2 v[78:79], v[98:99], off offset:144
	global_load_dwordx2 v[76:77], v[98:99], off offset:160
	global_load_dwordx2 v[74:75], v[98:99], off offset:176
	global_load_dwordx2 v[72:73], v[98:99], off offset:192
	global_load_dwordx2 v[70:71], v[98:99], off offset:208
	global_load_dwordx2 v[68:69], v[98:99], off offset:224
	global_load_dwordx2 v[66:67], v[98:99], off offset:240
	s_waitcnt vmcnt(15)
	v_lshlrev_b32_e32 v98, 16, v100
	v_mul_f32_e32 v102, 0xbfb8aa3b, v98
	v_exp_f32_e32 v102, v102
	v_and_b32_e32 v99, 0xffff0000, v100
	v_mul_f32_e32 v50, v50, v0
	v_lshlrev_b32_e32 v100, 16, v101
	v_add_f32_e32 v102, 1.0, v102
	v_rcp_f32_e32 v102, v102
	v_mul_f32_e32 v51, v51, v0
	v_and_b32_e32 v101, 0xffff0000, v101
	v_mul_f32_e32 v52, v52, v0
	v_mul_f32_e32 v98, v102, v98
	v_mul_f32_e32 v50, v50, v98
	v_mul_f32_e32 v98, 0xbfb8aa3b, v99
	v_exp_f32_e32 v98, v98
	v_mul_f32_e32 v53, v53, v0
	v_mul_f32_e32 v50, 0x41800000, v50
	v_med3_f32 v50, v50, s93, v223
	v_add_f32_e32 v98, 1.0, v98
	v_rcp_f32_e32 v98, v98
	s_nop 0
	v_mul_f32_e32 v98, v98, v99
	v_mul_f32_e32 v51, v51, v98
	v_mul_f32_e32 v98, 0xbfb8aa3b, v100
	v_exp_f32_e32 v98, v98
	v_mul_f32_e32 v51, 0x41800000, v51
	v_med3_f32 v51, v51, s93, v223
	v_add_f32_e32 v98, 1.0, v98
	v_rcp_f32_e32 v98, v98
	s_nop 0
	v_mul_f32_e32 v98, v98, v100
	v_mul_f32_e32 v52, v52, v98
	v_mul_f32_e32 v98, 0xbfb8aa3b, v101
	v_exp_f32_e32 v98, v98
	v_mul_f32_e32 v52, 0x41800000, v52
	v_add_f32_e32 v98, 1.0, v98
	v_rcp_f32_e32 v98, v98
	s_nop 0
	v_mul_f32_e32 v98, v98, v101
	v_mul_f32_e32 v53, v53, v98
	v_mov_b32_e32 v212, v1
	v_cvt_pk_fp8_f32 v212, v50, v51
	v_mul_f32_e32 v53, 0x41800000, v53
	v_med3_f32 v50, v52, s93, v223
	v_med3_f32 v51, v53, s93, v223
	v_cvt_pk_fp8_f32 v212, v50, v51 op_sel:[0,0,1]
	v_lshl_add_u64 v[50:51], v[88:89], 0, v[162:163]
	s_waitcnt vmcnt(14)
	v_lshlrev_b32_e32 v52, 16, v96
	v_and_b32_e32 v53, 0xffff0000, v96
	v_mul_f32_e32 v96, 0xbfb8aa3b, v52
	v_exp_f32_e32 v96, v96
	v_mul_f32_e32 v54, v54, v0
	v_lshlrev_b32_e32 v88, 16, v97
	v_and_b32_e32 v89, 0xffff0000, v97
	v_add_f32_e32 v96, 1.0, v96
	v_rcp_f32_e32 v96, v96
	s_nop 0
	v_mul_f32_e32 v52, v96, v52
	v_mul_f32_e32 v52, v54, v52
	v_mul_f32_e32 v54, 0xbfb8aa3b, v53
	v_exp_f32_e32 v54, v54
	v_mul_f32_e32 v52, 0x41800000, v52
	v_med3_f32 v52, v52, s93, v223
	v_add_f32_e32 v54, 1.0, v54
	v_rcp_f32_e32 v54, v54
	s_nop 0
	v_mul_f32_e32 v53, v54, v53
	v_mul_f32_e32 v54, v55, v0
	v_mul_f32_e32 v53, v54, v53
	v_mul_f32_e32 v54, 0xbfb8aa3b, v88
	v_exp_f32_e32 v54, v54
	v_mul_f32_e32 v55, v56, v0
	v_mul_f32_e32 v56, v57, v0
	v_mul_f32_e32 v53, 0x41800000, v53
	v_add_f32_e32 v54, 1.0, v54
	v_rcp_f32_e32 v54, v54
	v_med3_f32 v53, v53, s93, v223
	v_mul_f32_e32 v54, v54, v88
	v_mul_f32_e32 v54, v55, v54
	v_mul_f32_e32 v55, 0xbfb8aa3b, v89
	v_exp_f32_e32 v55, v55
	v_mul_f32_e32 v54, 0x41800000, v54
	v_add_f32_e32 v55, 1.0, v55
	v_rcp_f32_e32 v55, v55
	s_nop 0
	v_mul_f32_e32 v55, v55, v89
	v_mul_f32_e32 v55, v56, v55
	v_mov_b32_e32 v214, v1
	v_cvt_pk_fp8_f32 v214, v52, v53
	v_mul_f32_e32 v55, 0x41800000, v55
	v_med3_f32 v52, v54, s93, v223
	v_med3_f32 v53, v55, s93, v223
	v_cvt_pk_fp8_f32 v214, v52, v53 op_sel:[0,0,1]
	s_waitcnt vmcnt(13)
	v_lshlrev_b32_e32 v52, 16, v94
	v_mul_f32_e32 v56, 0xbfb8aa3b, v52
	v_exp_f32_e32 v56, v56
	v_and_b32_e32 v53, 0xffff0000, v94
	v_lshlrev_b32_e32 v54, 16, v95
	v_and_b32_e32 v55, 0xffff0000, v95
	v_add_f32_e32 v56, 1.0, v56
	v_rcp_f32_e32 v56, v56
	s_nop 0
	v_mul_f32_e32 v52, v56, v52
	v_mul_f32_e32 v56, v58, v0
	v_mul_f32_e32 v52, v56, v52
	v_mul_f32_e32 v56, 0xbfb8aa3b, v53
	v_exp_f32_e32 v56, v56
	v_mul_f32_e32 v52, 0x41800000, v52
	v_med3_f32 v52, v52, s93, v223
	v_add_f32_e32 v56, 1.0, v56
	v_rcp_f32_e32 v56, v56
	s_nop 0
	v_mul_f32_e32 v53, v56, v53
	v_mul_f32_e32 v56, v59, v0
	v_mul_f32_e32 v53, v56, v53
	v_mul_f32_e32 v56, 0xbfb8aa3b, v54
	v_exp_f32_e32 v56, v56
	v_mul_f32_e32 v53, 0x41800000, v53
	v_med3_f32 v53, v53, s93, v223
	v_add_f32_e32 v56, 1.0, v56
	v_rcp_f32_e32 v56, v56
	s_nop 0
	v_mul_f32_e32 v54, v56, v54
	v_mul_f32_e32 v56, v60, v0
	v_mul_f32_e32 v54, v56, v54
	v_mul_f32_e32 v56, 0xbfb8aa3b, v55
	v_exp_f32_e32 v56, v56
	v_mul_f32_e32 v54, 0x41800000, v54
	v_add_f32_e32 v56, 1.0, v56
	v_rcp_f32_e32 v56, v56
	s_nop 0
	v_mul_f32_e32 v55, v56, v55
	v_mul_f32_e32 v56, v61, v0
	v_mul_f32_e32 v55, v56, v55
	v_mov_b32_e32 v213, v1
	v_cvt_pk_fp8_f32 v213, v52, v53
	v_mul_f32_e32 v55, 0x41800000, v55
	v_med3_f32 v52, v54, s93, v223
	v_med3_f32 v53, v55, s93, v223
	v_cvt_pk_fp8_f32 v213, v52, v53 op_sel:[0,0,1]
	s_waitcnt vmcnt(12)
; DI float bf2f(unsigned b) { return __uint_as_float(b << 16); }
; template <int DQK, int W1, int DV, int VW, int MODE> ...
;     ...
; #pragma unroll
;   for (int cb = 0; cb < NCB; ++cb)
; #pragma unroll
;     for (int g = 0; g < 4; ++g) {
;       const int dv = 32 * cb + 8 * g + 4 * hi;
;       const u32x2 gg = ggv[cb * 4 + g];
;       float gv[4] = {bf2f(gg[0] & 0xffffu), bf2f(gg[0] >> 16), bf2f(gg[1] & 0xffffu), bf2f(gg[1] >> 16)};
;       float ov[4];
; #pragma unroll
;       for (int j = 0; j < 4; ++j) {
;         const float sg = gv[j] * __builtin_amdgcn_rcpf(1.f + __builtin_amdgcn_exp2f(-LOG2E * gv[j]));
;         ov[j] = o[cb][4 * g + j] * inv * sg;
;       }
;       *(unsigned*)((unsigned char*)yrow + dv) = pk4_fp8(ov[0] * Y_SCALE, ov[1] * Y_SCALE, ov[2] * Y_SCALE, ov[3] * Y_SCALE);
;       __builtin_amdgcn_sched_barrier(0);
;     }
	v_lshlrev_b32_e32 v52, 16, v92
	v_mul_f32_e32 v56, 0xbfb8aa3b, v52
	v_exp_f32_e32 v56, v56
	v_and_b32_e32 v53, 0xffff0000, v92
	v_lshlrev_b32_e32 v54, 16, v93
	v_and_b32_e32 v55, 0xffff0000, v93
	v_add_f32_e32 v56, 1.0, v56
	v_rcp_f32_e32 v56, v56
	s_nop 0
	v_mul_f32_e32 v52, v56, v52
	v_mul_f32_e32 v56, v62, v0
	v_mul_f32_e32 v52, v56, v52
	v_mul_f32_e32 v56, 0xbfb8aa3b, v53
	v_exp_f32_e32 v56, v56
	v_mul_f32_e32 v52, 0x41800000, v52
	v_med3_f32 v52, v52, s93, v223
	v_add_f32_e32 v56, 1.0, v56
	v_rcp_f32_e32 v56, v56
	s_nop 0
	v_mul_f32_e32 v53, v56, v53
	v_mul_f32_e32 v56, v63, v0
	v_mul_f32_e32 v53, v56, v53
	v_mul_f32_e32 v56, 0xbfb8aa3b, v54
	v_exp_f32_e32 v56, v56
	v_mul_f32_e32 v53, 0x41800000, v53
	v_med3_f32 v53, v53, s93, v223
	v_add_f32_e32 v56, 1.0, v56
	v_rcp_f32_e32 v56, v56
	s_nop 0
	v_mul_f32_e32 v54, v56, v54
	v_mul_f32_e32 v56, v64, v0
	v_mul_f32_e32 v54, v56, v54
	v_mul_f32_e32 v56, 0xbfb8aa3b, v55
	v_exp_f32_e32 v56, v56
	v_mul_f32_e32 v54, 0x41800000, v54
	v_add_f32_e32 v56, 1.0, v56
	v_rcp_f32_e32 v56, v56
	s_nop 0
	v_mul_f32_e32 v55, v56, v55
	v_mul_f32_e32 v56, v65, v0
	v_mul_f32_e32 v55, v56, v55
	v_mov_b32_e32 v215, v1
	v_cvt_pk_fp8_f32 v215, v52, v53
	v_mul_f32_e32 v55, 0x41800000, v55
	v_med3_f32 v52, v54, s93, v223
	v_med3_f32 v53, v55, s93, v223
	v_cvt_pk_fp8_f32 v215, v52, v53 op_sel:[0,0,1]
	v_and_b32_e32 v242, 32, v179
	v_lshrrev_b32_e32 v242, 3, v242
	v_lshl_add_u32 v242, v242, 1, v242
	v_mov_b32_e32 v243, 0
	v_lshl_add_u64 v[216:217], v[50:51], 0, v[242:243]
	s_nop 1
	v_permlane32_swap_b32_e32 v212, v213
	v_permlane32_swap_b32_e32 v214, v215
	global_store_dwordx4 v[216:217], v[212:215], off offset:2048
	s_waitcnt vmcnt(12)
	v_lshlrev_b32_e32 v52, 16, v90
	v_mul_f32_e32 v56, 0xbfb8aa3b, v52
	v_exp_f32_e32 v56, v56
	v_and_b32_e32 v53, 0xffff0000, v90
	v_mul_f32_e32 v34, v34, v0
	v_lshlrev_b32_e32 v54, 16, v91
	v_add_f32_e32 v56, 1.0, v56
	v_rcp_f32_e32 v56, v56
	v_mul_f32_e32 v35, v35, v0
	v_and_b32_e32 v55, 0xffff0000, v91
	v_mul_f32_e32 v36, v36, v0
	v_mul_f32_e32 v52, v56, v52
	v_mul_f32_e32 v34, v34, v52
	v_mul_f32_e32 v52, 0xbfb8aa3b, v53
	v_exp_f32_e32 v52, v52
	v_mul_f32_e32 v37, v37, v0
	v_mul_f32_e32 v34, 0x41800000, v34
	v_med3_f32 v34, v34, s93, v223
	v_add_f32_e32 v52, 1.0, v52
	v_rcp_f32_e32 v52, v52
	s_nop 0
	v_mul_f32_e32 v52, v52, v53
	v_mul_f32_e32 v35, v35, v52
	v_mul_f32_e32 v52, 0xbfb8aa3b, v54
	v_exp_f32_e32 v52, v52
	v_mul_f32_e32 v35, 0x41800000, v35
	v_med3_f32 v35, v35, s93, v223
	v_add_f32_e32 v52, 1.0, v52
	v_rcp_f32_e32 v52, v52
	s_nop 0
	v_mul_f32_e32 v52, v52, v54
	v_mul_f32_e32 v36, v36, v52
	v_mul_f32_e32 v52, 0xbfb8aa3b, v55
	v_exp_f32_e32 v52, v52
	v_mul_f32_e32 v36, 0x41800000, v36
	v_add_f32_e32 v52, 1.0, v52
	v_rcp_f32_e32 v52, v52
	s_nop 0
	v_mul_f32_e32 v52, v52, v55
	v_mul_f32_e32 v37, v37, v52
	v_mov_b32_e32 v212, v1
	v_cvt_pk_fp8_f32 v212, v34, v35
	v_mul_f32_e32 v37, 0x41800000, v37
	v_med3_f32 v34, v36, s93, v223
	v_med3_f32 v35, v37, s93, v223
	v_cvt_pk_fp8_f32 v212, v34, v35 op_sel:[0,0,1]
	s_waitcnt vmcnt(11)
	v_lshlrev_b32_e32 v34, 16, v86
	v_mul_f32_e32 v52, 0xbfb8aa3b, v34
	v_exp_f32_e32 v52, v52
	v_and_b32_e32 v35, 0xffff0000, v86
	v_mul_f32_e32 v38, v38, v0
	v_lshlrev_b32_e32 v36, 16, v87
	v_add_f32_e32 v52, 1.0, v52
	v_rcp_f32_e32 v52, v52
	v_and_b32_e32 v37, 0xffff0000, v87
	v_mul_f32_e32 v34, v52, v34
	v_mul_f32_e32 v34, v38, v34
	v_mul_f32_e32 v38, 0xbfb8aa3b, v35
	v_exp_f32_e32 v38, v38
	v_mul_f32_e32 v34, 0x41800000, v34
	v_med3_f32 v34, v34, s93, v223
	v_add_f32_e32 v38, 1.0, v38
	v_rcp_f32_e32 v38, v38
	s_nop 0
	v_mul_f32_e32 v35, v38, v35
	v_mul_f32_e32 v38, v39, v0
	v_mul_f32_e32 v35, v38, v35
	v_mul_f32_e32 v38, 0xbfb8aa3b, v36
	v_exp_f32_e32 v38, v38
	v_mul_f32_e32 v35, 0x41800000, v35
	v_med3_f32 v35, v35, s93, v223
	v_add_f32_e32 v38, 1.0, v38
	v_rcp_f32_e32 v38, v38
	s_nop 0
	v_mul_f32_e32 v36, v38, v36
	v_mul_f32_e32 v38, v40, v0
	v_mul_f32_e32 v36, v38, v36
	v_mul_f32_e32 v38, 0xbfb8aa3b, v37
	v_exp_f32_e32 v38, v38
	v_mul_f32_e32 v36, 0x41800000, v36
	v_add_f32_e32 v38, 1.0, v38
	v_rcp_f32_e32 v38, v38
	s_nop 0
	v_mul_f32_e32 v37, v38, v37
	v_mul_f32_e32 v38, v41, v0
	v_mul_f32_e32 v37, v38, v37
	v_mov_b32_e32 v214, v1
	v_cvt_pk_fp8_f32 v214, v34, v35
	v_mul_f32_e32 v37, 0x41800000, v37
	v_med3_f32 v34, v36, s93, v223
	v_med3_f32 v35, v37, s93, v223
	v_cvt_pk_fp8_f32 v214, v34, v35 op_sel:[0,0,1]
	s_waitcnt vmcnt(10)
	v_lshlrev_b32_e32 v34, 16, v84
	v_mul_f32_e32 v38, 0xbfb8aa3b, v34
	v_exp_f32_e32 v38, v38
	v_and_b32_e32 v35, 0xffff0000, v84
	v_lshlrev_b32_e32 v36, 16, v85
	v_and_b32_e32 v37, 0xffff0000, v85
	v_add_f32_e32 v38, 1.0, v38
	v_rcp_f32_e32 v38, v38
	s_nop 0
	v_mul_f32_e32 v34, v38, v34
	v_mul_f32_e32 v38, v42, v0
	v_mul_f32_e32 v34, v38, v34
	v_mul_f32_e32 v38, 0xbfb8aa3b, v35
	v_exp_f32_e32 v38, v38
	v_mul_f32_e32 v34, 0x41800000, v34
	v_med3_f32 v34, v34, s93, v223
	v_add_f32_e32 v38, 1.0, v38
	v_rcp_f32_e32 v38, v38
	s_nop 0
	v_mul_f32_e32 v35, v38, v35
	v_mul_f32_e32 v38, v43, v0
	v_mul_f32_e32 v35, v38, v35
	v_mul_f32_e32 v38, 0xbfb8aa3b, v36
	v_exp_f32_e32 v38, v38
	v_mul_f32_e32 v35, 0x41800000, v35
	v_med3_f32 v35, v35, s93, v223
	v_add_f32_e32 v38, 1.0, v38
	v_rcp_f32_e32 v38, v38
	s_nop 0
	v_mul_f32_e32 v36, v38, v36
	v_mul_f32_e32 v38, v44, v0
	v_mul_f32_e32 v36, v38, v36
	v_mul_f32_e32 v38, 0xbfb8aa3b, v37
	v_exp_f32_e32 v38, v38
	v_mul_f32_e32 v36, 0x41800000, v36
	v_add_f32_e32 v38, 1.0, v38
	v_rcp_f32_e32 v38, v38
	s_nop 0
	v_mul_f32_e32 v37, v38, v37
	v_mul_f32_e32 v38, v45, v0
	v_mul_f32_e32 v37, v38, v37
	v_mov_b32_e32 v213, v1
	v_cvt_pk_fp8_f32 v213, v34, v35
	v_mul_f32_e32 v37, 0x41800000, v37
	v_med3_f32 v34, v36, s93, v223
	v_med3_f32 v35, v37, s93, v223
	v_cvt_pk_fp8_f32 v213, v34, v35 op_sel:[0,0,1]
	s_waitcnt vmcnt(9)
; DI float bf2f(unsigned b) { return __uint_as_float(b << 16); }
; template <int DQK, int W1, int DV, int VW, int MODE> ...
;     ...
; #pragma unroll
;   for (int cb = 0; cb < NCB; ++cb)
; #pragma unroll
;     for (int g = 0; g < 4; ++g) {
;       const int dv = 32 * cb + 8 * g + 4 * hi;
;       const u32x2 gg = ggv[cb * 4 + g];
;       float gv[4] = {bf2f(gg[0] & 0xffffu), bf2f(gg[0] >> 16), bf2f(gg[1] & 0xffffu), bf2f(gg[1] >> 16)};
;       float ov[4];
; #pragma unroll
;       for (int j = 0; j < 4; ++j) {
;         const float sg = gv[j] * __builtin_amdgcn_rcpf(1.f + __builtin_amdgcn_exp2f(-LOG2E * gv[j]));
;         ov[j] = o[cb][4 * g + j] * inv * sg;
;       }
;       *(unsigned*)((unsigned char*)yrow + dv) = pk4_fp8(ov[0] * Y_SCALE, ov[1] * Y_SCALE, ov[2] * Y_SCALE, ov[3] * Y_SCALE);
;       __builtin_amdgcn_sched_barrier(0);
;     }
	v_lshlrev_b32_e32 v34, 16, v82
	v_mul_f32_e32 v38, 0xbfb8aa3b, v34
	v_exp_f32_e32 v38, v38
	v_and_b32_e32 v35, 0xffff0000, v82
	v_lshlrev_b32_e32 v36, 16, v83
	v_and_b32_e32 v37, 0xffff0000, v83
	v_add_f32_e32 v38, 1.0, v38
	v_rcp_f32_e32 v38, v38
	s_nop 0
	v_mul_f32_e32 v34, v38, v34
	v_mul_f32_e32 v38, v46, v0
	v_mul_f32_e32 v34, v38, v34
	v_mul_f32_e32 v38, 0xbfb8aa3b, v35
	v_exp_f32_e32 v38, v38
	v_mul_f32_e32 v34, 0x41800000, v34
	v_med3_f32 v34, v34, s93, v223
	v_add_f32_e32 v38, 1.0, v38
	v_rcp_f32_e32 v38, v38
	s_nop 0
	v_mul_f32_e32 v35, v38, v35
	v_mul_f32_e32 v38, v47, v0
	v_mul_f32_e32 v35, v38, v35
	v_mul_f32_e32 v38, 0xbfb8aa3b, v36
	v_exp_f32_e32 v38, v38
	v_mul_f32_e32 v35, 0x41800000, v35
	v_med3_f32 v35, v35, s93, v223
	v_add_f32_e32 v38, 1.0, v38
	v_rcp_f32_e32 v38, v38
	s_nop 0
	v_mul_f32_e32 v36, v38, v36
	v_mul_f32_e32 v38, v48, v0
	v_mul_f32_e32 v36, v38, v36
	v_mul_f32_e32 v38, 0xbfb8aa3b, v37
	v_exp_f32_e32 v38, v38
	v_mul_f32_e32 v36, 0x41800000, v36
	v_add_f32_e32 v38, 1.0, v38
	v_rcp_f32_e32 v38, v38
	s_nop 0
	v_mul_f32_e32 v37, v38, v37
	v_mul_f32_e32 v38, v49, v0
	v_mul_f32_e32 v37, v38, v37
	v_mov_b32_e32 v215, v1
	v_cvt_pk_fp8_f32 v215, v34, v35
	v_mul_f32_e32 v37, 0x41800000, v37
	v_med3_f32 v34, v36, s93, v223
	v_med3_f32 v35, v37, s93, v223
	v_cvt_pk_fp8_f32 v215, v34, v35 op_sel:[0,0,1]
	s_nop 1
	v_permlane32_swap_b32_e32 v212, v213
	v_permlane32_swap_b32_e32 v214, v215
	global_store_dwordx4 v[216:217], v[212:215], off offset:2080
	s_waitcnt vmcnt(9)
	v_lshlrev_b32_e32 v34, 16, v80
	v_mul_f32_e32 v38, 0xbfb8aa3b, v34
	v_exp_f32_e32 v38, v38
	v_and_b32_e32 v35, 0xffff0000, v80
	v_mul_f32_e32 v18, v18, v0
	v_lshlrev_b32_e32 v36, 16, v81
	v_add_f32_e32 v38, 1.0, v38
	v_rcp_f32_e32 v38, v38
	v_mul_f32_e32 v19, v19, v0
	v_and_b32_e32 v37, 0xffff0000, v81
	v_mul_f32_e32 v20, v20, v0
	v_mul_f32_e32 v34, v38, v34
	v_mul_f32_e32 v18, v18, v34
	v_mul_f32_e32 v34, 0xbfb8aa3b, v35
	v_exp_f32_e32 v34, v34
	v_mul_f32_e32 v21, v21, v0
	v_mul_f32_e32 v18, 0x41800000, v18
	v_med3_f32 v18, v18, s93, v223
	v_add_f32_e32 v34, 1.0, v34
	v_rcp_f32_e32 v34, v34
	s_nop 0
	v_mul_f32_e32 v34, v34, v35
	v_mul_f32_e32 v19, v19, v34
	v_mul_f32_e32 v34, 0xbfb8aa3b, v36
	v_exp_f32_e32 v34, v34
	v_mul_f32_e32 v19, 0x41800000, v19
	v_med3_f32 v19, v19, s93, v223
	v_add_f32_e32 v34, 1.0, v34
	v_rcp_f32_e32 v34, v34
	s_nop 0
	v_mul_f32_e32 v34, v34, v36
	v_mul_f32_e32 v20, v20, v34
	v_mul_f32_e32 v34, 0xbfb8aa3b, v37
	v_exp_f32_e32 v34, v34
	v_mul_f32_e32 v20, 0x41800000, v20
	v_add_f32_e32 v34, 1.0, v34
	v_rcp_f32_e32 v34, v34
	s_nop 0
	v_mul_f32_e32 v34, v34, v37
	v_mul_f32_e32 v21, v21, v34
	v_mov_b32_e32 v212, v1
	v_cvt_pk_fp8_f32 v212, v18, v19
	v_mul_f32_e32 v21, 0x41800000, v21
	v_med3_f32 v18, v20, s93, v223
	v_med3_f32 v19, v21, s93, v223
	v_cvt_pk_fp8_f32 v212, v18, v19 op_sel:[0,0,1]
	s_waitcnt vmcnt(8)
	v_lshlrev_b32_e32 v18, 16, v78
	v_mul_f32_e32 v34, 0xbfb8aa3b, v18
	v_exp_f32_e32 v34, v34
	v_and_b32_e32 v19, 0xffff0000, v78
	v_mul_f32_e32 v22, v22, v0
	v_lshlrev_b32_e32 v20, 16, v79
	v_add_f32_e32 v34, 1.0, v34
	v_rcp_f32_e32 v34, v34
	v_and_b32_e32 v21, 0xffff0000, v79
	v_mul_f32_e32 v18, v34, v18
	v_mul_f32_e32 v18, v22, v18
	v_mul_f32_e32 v22, 0xbfb8aa3b, v19
	v_exp_f32_e32 v22, v22
	v_mul_f32_e32 v18, 0x41800000, v18
	v_med3_f32 v18, v18, s93, v223
	v_add_f32_e32 v22, 1.0, v22
	v_rcp_f32_e32 v22, v22
	s_nop 0
	v_mul_f32_e32 v19, v22, v19
	v_mul_f32_e32 v22, v23, v0
	v_mul_f32_e32 v19, v22, v19
	v_mul_f32_e32 v22, 0xbfb8aa3b, v20
	v_exp_f32_e32 v22, v22
	v_mul_f32_e32 v19, 0x41800000, v19
	v_med3_f32 v19, v19, s93, v223
	v_add_f32_e32 v22, 1.0, v22
	v_rcp_f32_e32 v22, v22
	s_nop 0
	v_mul_f32_e32 v20, v22, v20
	v_mul_f32_e32 v22, v24, v0
	v_mul_f32_e32 v20, v22, v20
	v_mul_f32_e32 v22, 0xbfb8aa3b, v21
	v_exp_f32_e32 v22, v22
	v_mul_f32_e32 v20, 0x41800000, v20
	v_add_f32_e32 v22, 1.0, v22
	v_rcp_f32_e32 v22, v22
	s_nop 0
	v_mul_f32_e32 v21, v22, v21
	v_mul_f32_e32 v22, v25, v0
	v_mul_f32_e32 v21, v22, v21
	v_mov_b32_e32 v214, v1
	v_cvt_pk_fp8_f32 v214, v18, v19
	v_mul_f32_e32 v21, 0x41800000, v21
	v_med3_f32 v18, v20, s93, v223
	v_med3_f32 v19, v21, s93, v223
	v_cvt_pk_fp8_f32 v214, v18, v19 op_sel:[0,0,1]
	s_waitcnt vmcnt(7)
	v_lshlrev_b32_e32 v18, 16, v76
	v_mul_f32_e32 v22, 0xbfb8aa3b, v18
	v_exp_f32_e32 v22, v22
	v_and_b32_e32 v19, 0xffff0000, v76
	v_lshlrev_b32_e32 v20, 16, v77
	v_and_b32_e32 v21, 0xffff0000, v77
	v_add_f32_e32 v22, 1.0, v22
	v_rcp_f32_e32 v22, v22
	s_nop 0
	v_mul_f32_e32 v18, v22, v18
	v_mul_f32_e32 v22, v26, v0
	v_mul_f32_e32 v18, v22, v18
	v_mul_f32_e32 v22, 0xbfb8aa3b, v19
	v_exp_f32_e32 v22, v22
	v_mul_f32_e32 v18, 0x41800000, v18
	v_med3_f32 v18, v18, s93, v223
	v_add_f32_e32 v22, 1.0, v22
	v_rcp_f32_e32 v22, v22
	s_nop 0
	v_mul_f32_e32 v19, v22, v19
	v_mul_f32_e32 v22, v27, v0
	v_mul_f32_e32 v19, v22, v19
	v_mul_f32_e32 v22, 0xbfb8aa3b, v20
	v_exp_f32_e32 v22, v22
	v_mul_f32_e32 v19, 0x41800000, v19
	v_med3_f32 v19, v19, s93, v223
	v_add_f32_e32 v22, 1.0, v22
	v_rcp_f32_e32 v22, v22
	s_nop 0
	v_mul_f32_e32 v20, v22, v20
	v_mul_f32_e32 v22, v28, v0
	v_mul_f32_e32 v20, v22, v20
	v_mul_f32_e32 v22, 0xbfb8aa3b, v21
	v_exp_f32_e32 v22, v22
	v_mul_f32_e32 v20, 0x41800000, v20
	v_add_f32_e32 v22, 1.0, v22
	v_rcp_f32_e32 v22, v22
	s_nop 0
	v_mul_f32_e32 v21, v22, v21
	v_mul_f32_e32 v22, v29, v0
	v_mul_f32_e32 v21, v22, v21
	v_mov_b32_e32 v213, v1
	v_cvt_pk_fp8_f32 v213, v18, v19
	v_mul_f32_e32 v21, 0x41800000, v21
	v_med3_f32 v18, v20, s93, v223
	v_med3_f32 v19, v21, s93, v223
	v_cvt_pk_fp8_f32 v213, v18, v19 op_sel:[0,0,1]
	s_waitcnt vmcnt(6)
; DI float bf2f(unsigned b) { return __uint_as_float(b << 16); }
; template <int DQK, int W1, int DV, int VW, int MODE> ...
;     ...
; #pragma unroll
;   for (int cb = 0; cb < NCB; ++cb)
; #pragma unroll
;     for (int g = 0; g < 4; ++g) {
;       const int dv = 32 * cb + 8 * g + 4 * hi;
;       const u32x2 gg = ggv[cb * 4 + g];
;       float gv[4] = {bf2f(gg[0] & 0xffffu), bf2f(gg[0] >> 16), bf2f(gg[1] & 0xffffu), bf2f(gg[1] >> 16)};
;       float ov[4];
; #pragma unroll
;       for (int j = 0; j < 4; ++j) {
;         const float sg = gv[j] * __builtin_amdgcn_rcpf(1.f + __builtin_amdgcn_exp2f(-LOG2E * gv[j]));
;         ov[j] = o[cb][4 * g + j] * inv * sg;
;       }
;       *(unsigned*)((unsigned char*)yrow + dv) = pk4_fp8(ov[0] * Y_SCALE, ov[1] * Y_SCALE, ov[2] * Y_SCALE, ov[3] * Y_SCALE);
;       __builtin_amdgcn_sched_barrier(0);
;     }
	v_lshlrev_b32_e32 v18, 16, v74
	v_mul_f32_e32 v22, 0xbfb8aa3b, v18
	v_exp_f32_e32 v22, v22
	v_and_b32_e32 v19, 0xffff0000, v74
	v_lshlrev_b32_e32 v20, 16, v75
	v_and_b32_e32 v21, 0xffff0000, v75
	v_add_f32_e32 v22, 1.0, v22
	v_rcp_f32_e32 v22, v22
	s_nop 0
	v_mul_f32_e32 v18, v22, v18
	v_mul_f32_e32 v22, v30, v0
	v_mul_f32_e32 v18, v22, v18
	v_mul_f32_e32 v22, 0xbfb8aa3b, v19
	v_exp_f32_e32 v22, v22
	v_mul_f32_e32 v18, 0x41800000, v18
	v_med3_f32 v18, v18, s93, v223
	v_add_f32_e32 v22, 1.0, v22
	v_rcp_f32_e32 v22, v22
	s_nop 0
	v_mul_f32_e32 v19, v22, v19
	v_mul_f32_e32 v22, v31, v0
	v_mul_f32_e32 v19, v22, v19
	v_mul_f32_e32 v22, 0xbfb8aa3b, v20
	v_exp_f32_e32 v22, v22
	v_mul_f32_e32 v19, 0x41800000, v19
	v_med3_f32 v19, v19, s93, v223
	v_add_f32_e32 v22, 1.0, v22
	v_rcp_f32_e32 v22, v22
	s_nop 0
	v_mul_f32_e32 v20, v22, v20
	v_mul_f32_e32 v22, v32, v0
	v_mul_f32_e32 v20, v22, v20
	v_mul_f32_e32 v22, 0xbfb8aa3b, v21
	v_exp_f32_e32 v22, v22
	v_mul_f32_e32 v20, 0x41800000, v20
	v_add_f32_e32 v22, 1.0, v22
	v_rcp_f32_e32 v22, v22
	s_nop 0
	v_mul_f32_e32 v21, v22, v21
	v_mul_f32_e32 v22, v33, v0
	v_mul_f32_e32 v21, v22, v21
	v_mov_b32_e32 v215, v1
	v_cvt_pk_fp8_f32 v215, v18, v19
	v_mul_f32_e32 v21, 0x41800000, v21
	v_med3_f32 v18, v20, s93, v223
	v_med3_f32 v19, v21, s93, v223
	v_cvt_pk_fp8_f32 v215, v18, v19 op_sel:[0,0,1]
	s_nop 1
	v_permlane32_swap_b32_e32 v212, v213
	v_permlane32_swap_b32_e32 v214, v215
	global_store_dwordx4 v[216:217], v[212:215], off offset:2112
	s_waitcnt vmcnt(6)
	v_lshlrev_b32_e32 v18, 16, v72
	v_mul_f32_e32 v22, 0xbfb8aa3b, v18
	v_exp_f32_e32 v22, v22
	v_and_b32_e32 v19, 0xffff0000, v72
	v_mul_f32_e32 v2, v2, v0
	v_lshlrev_b32_e32 v20, 16, v73
	v_add_f32_e32 v22, 1.0, v22
	v_rcp_f32_e32 v22, v22
	v_mul_f32_e32 v3, v3, v0
	v_and_b32_e32 v21, 0xffff0000, v73
	v_mul_f32_e32 v4, v4, v0
	v_mul_f32_e32 v18, v22, v18
	v_mul_f32_e32 v2, v2, v18
	v_mul_f32_e32 v18, 0xbfb8aa3b, v19
	v_exp_f32_e32 v18, v18
	v_mul_f32_e32 v5, v5, v0
	v_mul_f32_e32 v2, 0x41800000, v2
	v_med3_f32 v2, v2, s93, v223
	v_add_f32_e32 v18, 1.0, v18
	v_rcp_f32_e32 v18, v18
	s_nop 0
	v_mul_f32_e32 v18, v18, v19
	v_mul_f32_e32 v3, v3, v18
	v_mul_f32_e32 v18, 0xbfb8aa3b, v20
	v_exp_f32_e32 v18, v18
	v_mul_f32_e32 v3, 0x41800000, v3
	v_med3_f32 v3, v3, s93, v223
	v_add_f32_e32 v18, 1.0, v18
	v_rcp_f32_e32 v18, v18
	s_nop 0
	v_mul_f32_e32 v18, v18, v20
	v_mul_f32_e32 v4, v4, v18
	v_mul_f32_e32 v18, 0xbfb8aa3b, v21
	v_exp_f32_e32 v18, v18
	v_mul_f32_e32 v4, 0x41800000, v4
	v_add_f32_e32 v18, 1.0, v18
	v_rcp_f32_e32 v18, v18
	s_nop 0
	v_mul_f32_e32 v18, v18, v21
	v_mul_f32_e32 v5, v5, v18
	v_mov_b32_e32 v212, v1
	v_cvt_pk_fp8_f32 v212, v2, v3
	v_mul_f32_e32 v5, 0x41800000, v5
	v_med3_f32 v2, v4, s93, v223
	v_med3_f32 v3, v5, s93, v223
	v_cvt_pk_fp8_f32 v212, v2, v3 op_sel:[0,0,1]
	s_waitcnt vmcnt(5)
	v_lshlrev_b32_e32 v2, 16, v70
	v_mul_f32_e32 v18, 0xbfb8aa3b, v2
	v_exp_f32_e32 v18, v18
	v_and_b32_e32 v3, 0xffff0000, v70
	v_mul_f32_e32 v6, v6, v0
	v_lshlrev_b32_e32 v4, 16, v71
	v_add_f32_e32 v18, 1.0, v18
	v_rcp_f32_e32 v18, v18
	v_and_b32_e32 v5, 0xffff0000, v71
	v_mul_f32_e32 v2, v18, v2
	v_mul_f32_e32 v2, v6, v2
	v_mul_f32_e32 v6, 0xbfb8aa3b, v3
	v_exp_f32_e32 v6, v6
	v_mul_f32_e32 v2, 0x41800000, v2
	v_med3_f32 v2, v2, s93, v223
	v_add_f32_e32 v6, 1.0, v6
	v_rcp_f32_e32 v6, v6
	s_nop 0
	v_mul_f32_e32 v3, v6, v3
	v_mul_f32_e32 v6, v7, v0
	v_mul_f32_e32 v3, v6, v3
	v_mul_f32_e32 v6, 0xbfb8aa3b, v4
	v_exp_f32_e32 v6, v6
	v_mul_f32_e32 v3, 0x41800000, v3
	v_med3_f32 v3, v3, s93, v223
	v_add_f32_e32 v6, 1.0, v6
	v_rcp_f32_e32 v6, v6
	s_nop 0
	v_mul_f32_e32 v4, v6, v4
	v_mul_f32_e32 v6, v8, v0
	v_mul_f32_e32 v4, v6, v4
	v_mul_f32_e32 v6, 0xbfb8aa3b, v5
	v_exp_f32_e32 v6, v6
	v_mul_f32_e32 v4, 0x41800000, v4
	v_add_f32_e32 v6, 1.0, v6
	v_rcp_f32_e32 v6, v6
	s_nop 0
	v_mul_f32_e32 v5, v6, v5
	v_mul_f32_e32 v6, v9, v0
	v_mul_f32_e32 v5, v6, v5
	v_mov_b32_e32 v214, v1
	v_cvt_pk_fp8_f32 v214, v2, v3
	v_mul_f32_e32 v5, 0x41800000, v5
	v_med3_f32 v2, v4, s93, v223
	v_med3_f32 v3, v5, s93, v223
	v_cvt_pk_fp8_f32 v214, v2, v3 op_sel:[0,0,1]
	s_waitcnt vmcnt(4)
	v_lshlrev_b32_e32 v2, 16, v68
	v_mul_f32_e32 v6, 0xbfb8aa3b, v2
	v_exp_f32_e32 v6, v6
	v_and_b32_e32 v3, 0xffff0000, v68
	v_lshlrev_b32_e32 v4, 16, v69
	v_and_b32_e32 v5, 0xffff0000, v69
	v_add_f32_e32 v6, 1.0, v6
	v_rcp_f32_e32 v6, v6
	s_nop 0
	v_mul_f32_e32 v2, v6, v2
	v_mul_f32_e32 v6, v10, v0
	v_mul_f32_e32 v2, v6, v2
	v_mul_f32_e32 v6, 0xbfb8aa3b, v3
	v_exp_f32_e32 v6, v6
	v_mul_f32_e32 v2, 0x41800000, v2
	v_med3_f32 v2, v2, s93, v223
	v_add_f32_e32 v6, 1.0, v6
	v_rcp_f32_e32 v6, v6
	s_nop 0
	v_mul_f32_e32 v3, v6, v3
	v_mul_f32_e32 v6, v11, v0
	v_mul_f32_e32 v3, v6, v3
	v_mul_f32_e32 v6, 0xbfb8aa3b, v4
	v_exp_f32_e32 v6, v6
	v_mul_f32_e32 v3, 0x41800000, v3
	v_med3_f32 v3, v3, s93, v223
	v_add_f32_e32 v6, 1.0, v6
	v_rcp_f32_e32 v6, v6
	s_nop 0
	v_mul_f32_e32 v4, v6, v4
	v_mul_f32_e32 v6, v12, v0
	v_mul_f32_e32 v4, v6, v4
	v_mul_f32_e32 v6, 0xbfb8aa3b, v5
	v_exp_f32_e32 v6, v6
	v_mul_f32_e32 v4, 0x41800000, v4
	v_add_f32_e32 v6, 1.0, v6
	v_rcp_f32_e32 v6, v6
	s_nop 0
	v_mul_f32_e32 v5, v6, v5
	v_mul_f32_e32 v6, v13, v0
	v_mul_f32_e32 v5, v6, v5
	v_mov_b32_e32 v213, v1
	v_cvt_pk_fp8_f32 v213, v2, v3
	v_mul_f32_e32 v5, 0x41800000, v5
	v_med3_f32 v2, v4, s93, v223
	v_med3_f32 v3, v5, s93, v223
	v_cvt_pk_fp8_f32 v213, v2, v3 op_sel:[0,0,1]
	s_waitcnt vmcnt(3)
	v_lshlrev_b32_e32 v2, 16, v66
	v_mul_f32_e32 v6, 0xbfb8aa3b, v2
	v_exp_f32_e32 v6, v6
	v_and_b32_e32 v3, 0xffff0000, v66
	v_lshlrev_b32_e32 v4, 16, v67
	v_and_b32_e32 v5, 0xffff0000, v67
	v_add_f32_e32 v6, 1.0, v6
	v_rcp_f32_e32 v6, v6
	s_nop 0
	v_mul_f32_e32 v2, v6, v2
	v_mul_f32_e32 v6, v14, v0
	v_mul_f32_e32 v2, v6, v2
	v_mul_f32_e32 v6, 0xbfb8aa3b, v3
	v_exp_f32_e32 v6, v6
	v_mul_f32_e32 v2, 0x41800000, v2
	v_med3_f32 v2, v2, s93, v223
	v_add_f32_e32 v6, 1.0, v6
	v_rcp_f32_e32 v6, v6
	s_nop 0
	v_mul_f32_e32 v3, v6, v3
	v_mul_f32_e32 v6, v15, v0
	v_mul_f32_e32 v3, v6, v3
	v_mul_f32_e32 v6, 0xbfb8aa3b, v4
	v_exp_f32_e32 v6, v6
	v_mul_f32_e32 v3, 0x41800000, v3
	v_med3_f32 v3, v3, s93, v223
	v_add_f32_e32 v6, 1.0, v6
	v_rcp_f32_e32 v6, v6
	s_nop 0
	v_mul_f32_e32 v4, v6, v4
	v_mul_f32_e32 v6, v16, v0
	v_mul_f32_e32 v4, v6, v4
	v_mul_f32_e32 v6, 0xbfb8aa3b, v5
	v_exp_f32_e32 v6, v6
	v_mul_f32_e32 v0, v17, v0
	v_mul_f32_e32 v4, 0x41800000, v4
	v_add_f32_e32 v6, 1.0, v6
	v_rcp_f32_e32 v6, v6
	s_nop 0
	v_mul_f32_e32 v5, v6, v5
	v_mul_f32_e32 v0, v0, v5
	v_mov_b32_e32 v215, v1
	v_cvt_pk_fp8_f32 v215, v2, v3
	v_mul_f32_e32 v0, 0x41800000, v0
	v_med3_f32 v2, v4, s93, v223
	v_med3_f32 v0, v0, s93, v223
	v_cvt_pk_fp8_f32 v215, v2, v0 op_sel:[0,0,1]
	s_nop 1
	v_permlane32_swap_b32_e32 v212, v213
	v_permlane32_swap_b32_e32 v214, v215
	global_store_dwordx4 v[216:217], v[212:215], off offset:2144
	s_branch .LBB0_1239

; template <int DQK, int W1, int DV, int VW, int MODE> ...
;     ...
;         f32x16 e0 = s[0], e1 = s[1];
;         if (MODE != 0) { const float nm = -m; e0 = e0 + nm; e1 = e1 + nm; }
; #pragma unroll
;         for (int i = 0; i < 16; ++i) { e0[i] = __builtin_amdgcn_exp2f(e0[i]); e1[i] = __builtin_amdgcn_exp2f(e1[i]); }
;         s[0] = e0; s[1] = e1;
;         const f32x16 sm = e0 + e1;
;         typedef __attribute__((ext_vector_type(8))) float f32x8;
;         const f32x8 h8 = sm.lo + sm.hi;
;         const f32x4 h4 = h8.lo + h8.hi;
;         const f32x2 h2 = h4.lo + h4.hi;
;         l += h2[0] + h2[1];
;       }
;       bf16x8 pb[2][2];
; #pragma unroll
;       for (int n = 0; n < 2; ++n)
; #pragma unroll
;         for (int s2 = 0; s2 < 2; ++s2) {
;           u32x4 pw = {pk2(s[n][8 * s2 + 0], s[n][8 * s2 + 1]), pk2(s[n][8 * s2 + 2], s[n][8 * s2 + 3]),
;                       pk2(s[n][8 * s2 + 4], s[n][8 * s2 + 5]), pk2(s[n][8 * s2 + 6], s[n][8 * s2 + 7])};
;           pb[n][s2] = __builtin_bit_cast(bf16x8, pw);
;         }
;       pv_block<0>(o[0], bufa + vlane, pb);
;       if constexpr (NCB > 1) pv_block<1>(o[1], bufa + vlane, pb);
;       if constexpr (NCB > 2) pv_block<2>(o[2], bufa + vlane, pb);
;       if constexpr (NCB > 3) pv_block<3>(o[3], bufa + vlane, pb);
;     }
;     asm volatile("s_waitcnt vmcnt(0)" ::: "memory");
;     __syncthreads();
.LBB0_1319:
	v_mov_b32_e32 v105, v104
	v_mov_b32_e32 v68, v104
	v_mov_b32_e32 v69, v104
	v_mov_b32_e32 v70, v104
	v_mov_b32_e32 v71, v104
	v_mov_b32_e32 v72, v104
	v_mov_b32_e32 v73, v104
	v_mov_b32_e32 v74, v104
	v_mov_b32_e32 v75, v104
	v_mov_b32_e32 v76, v104
	v_mov_b32_e32 v77, v104
	v_mov_b32_e32 v78, v104
	v_mov_b32_e32 v79, v104
	v_mov_b32_e32 v80, v104
	v_mov_b32_e32 v81, v104
	v_pk_add_f32 v[64:65], v[64:65], v[80:81]
	v_pk_add_f32 v[62:63], v[62:63], v[78:79]
	v_pk_add_f32 v[60:61], v[60:61], v[76:77]
	v_pk_add_f32 v[58:59], v[58:59], v[74:75]
	v_pk_add_f32 v[56:57], v[56:57], v[72:73]
	v_pk_add_f32 v[54:55], v[54:55], v[70:71]
	v_pk_add_f32 v[52:53], v[52:53], v[68:69]
	v_pk_add_f32 v[50:51], v[50:51], v[104:105]
	v_pk_add_f32 v[48:49], v[48:49], v[80:81]
	v_pk_add_f32 v[46:47], v[46:47], v[78:79]
	v_pk_add_f32 v[44:45], v[44:45], v[76:77]
	v_pk_add_f32 v[42:43], v[42:43], v[74:75]
	v_pk_add_f32 v[66:67], v[66:67], v[72:73]
	v_pk_add_f32 v[38:39], v[38:39], v[70:71]
	v_pk_add_f32 v[36:37], v[36:37], v[68:69]
	v_pk_add_f32 v[34:35], v[34:35], v[104:105]
	v_exp_f32_e32 v50, v50
	v_exp_f32_e32 v68, v34
	v_exp_f32_e32 v51, v51
	v_exp_f32_e32 v69, v35
	v_exp_f32_e32 v52, v52
	v_exp_f32_e32 v70, v36
	v_exp_f32_e32 v53, v53
	v_exp_f32_e32 v71, v37
	v_exp_f32_e32 v36, v54
	v_exp_f32_e32 v38, v38
	v_exp_f32_e32 v37, v55
	v_exp_f32_e32 v39, v39
	v_exp_f32_e32 v54, v56
	v_exp_f32_e32 v56, v66
	v_exp_f32_e32 v55, v57
	v_exp_f32_e32 v57, v67
	v_exp_f32_e32 v58, v58
	v_exp_f32_e32 v66, v42
	v_exp_f32_e32 v59, v59
	v_exp_f32_e32 v67, v43
	v_exp_f32_e32 v60, v60
	v_exp_f32_e32 v72, v44
	v_exp_f32_e32 v61, v61
	v_exp_f32_e32 v73, v45
	v_exp_f32_e32 v44, v62
	v_exp_f32_e32 v62, v46
	v_exp_f32_e32 v45, v63
	v_exp_f32_e32 v63, v47
	v_exp_f32_e32 v46, v64
	v_exp_f32_e32 v64, v48
	v_exp_f32_e32 v47, v65
	v_exp_f32_e32 v65, v49
	v_mov_b64_e32 v[40:41], s[82:83]
	v_mad_u64_u32 v[40:41], s[0:1], v86, s34, v[40:41]
	v_mad_i32_i24 v41, v87, s34, v41
	v_pk_add_f32 v[34:35], v[60:61], v[72:73]
	v_pk_add_f32 v[42:43], v[52:53], v[70:71]
	v_pk_add_f32 v[48:49], v[46:47], v[64:65]
	v_pk_add_f32 v[74:75], v[54:55], v[56:57]
	v_pk_add_f32 v[76:77], v[50:51], v[68:69]
	v_pk_add_f32 v[78:79], v[58:59], v[66:67]
	v_pk_add_f32 v[80:81], v[44:45], v[62:63]
	v_pk_add_f32 v[86:87], v[36:37], v[38:39]
	v_pk_add_f32 v[76:77], v[76:77], v[78:79]
	v_pk_add_f32 v[80:81], v[86:87], v[80:81]
	v_pk_add_f32 v[48:49], v[74:75], v[48:49]
	v_pk_add_f32 v[34:35], v[42:43], v[34:35]
	v_pk_add_f32 v[42:43], v[76:77], v[80:81]
	v_pk_add_f32 v[34:35], v[34:35], v[48:49]
	v_cvt_pk_bf16_f32 v36, v36, v37
	v_pk_add_f32 v[34:35], v[42:43], v[34:35]
	v_cvt_pk_bf16_f32 v37, v54, v55
	v_add_f32_e32 v74, v34, v35
	v_cvt_pk_bf16_f32 v34, v50, v51
	v_cvt_pk_bf16_f32 v35, v52, v53
	v_cvt_pk_bf16_f32 v42, v58, v59
	v_cvt_pk_bf16_f32 v43, v60, v61
	v_cvt_pk_bf16_f32 v44, v44, v45
	v_cvt_pk_bf16_f32 v45, v46, v47
	v_cvt_pk_bf16_f32 v46, v68, v69
	v_cvt_pk_bf16_f32 v49, v56, v57
	v_cvt_pk_bf16_f32 v50, v66, v67
	v_cvt_pk_bf16_f32 v52, v62, v63
	v_cvt_pk_bf16_f32 v53, v64, v65
	ds_read_b64_tr_b16 v[66:67], v101 offset:0
	ds_read_b64_tr_b16 v[68:69], v101 offset:0x200
	ds_read_b64_tr_b16 v[62:63], v101 offset:0x400
	ds_read_b64_tr_b16 v[64:65], v101 offset:0x600
	ds_read_b64_tr_b16 v[58:59], v101 offset:0x800
	ds_read_b64_tr_b16 v[60:61], v101 offset:0xa00
	ds_read_b64_tr_b16 v[54:55], v101 offset:0xc00
	ds_read_b64_tr_b16 v[56:57], v101 offset:0xe00
	s_waitcnt lgkmcnt(0)
	v_cvt_pk_bf16_f32 v47, v70, v71
	v_mfma_f32_32x32x16_bf16 v[18:33], v[66:69], v[34:37], v[18:33]
	v_cvt_pk_bf16_f32 v48, v38, v39
	v_cvt_pk_bf16_f32 v51, v72, v73
	v_add_f32_e32 v38, v106, v74
	s_mov_b64 s[0:1], 0x1c00
	v_lshl_add_u64 v[40:41], v[40:41], 0, s[18:19]
	v_mov_b32_e32 v83, v1
	v_mfma_f32_32x32x16_bf16 v[18:33], v[62:65], v[42:45], v[18:33]
	v_mfma_f32_32x32x16_bf16 v[18:33], v[58:61], v[46:49], v[18:33]
	v_mfma_f32_32x32x16_bf16 v[18:33], v[54:57], v[50:53], v[18:33]
	ds_read_b64_tr_b16 v[66:67], v101 offset:0x1000
	ds_read_b64_tr_b16 v[68:69], v101 offset:0x1200
	ds_read_b64_tr_b16 v[62:63], v101 offset:0x1400
	ds_read_b64_tr_b16 v[64:65], v101 offset:0x1600
	ds_read_b64_tr_b16 v[58:59], v101 offset:0x1800
	ds_read_b64_tr_b16 v[60:61], v101 offset:0x1a00
	ds_read_b64_tr_b16 v[54:55], v101 offset:0x1c00
	ds_read_b64_tr_b16 v[56:57], v101 offset:0x1e00
	s_waitcnt lgkmcnt(0)
	s_waitcnt vmcnt(0)
	s_barrier
; DI float bf2f(unsigned b) { return __uint_as_float(b << 16); }
; template <int DQK, int W1, int DV, int VW, int MODE> ...
;     ...
;   const float inv = __builtin_amdgcn_rcpf(xhalf_sum(l));
;   u32x2 ggv[NCB * 4];
; #pragma unroll
;   for (int cb = 0; cb < NCB; ++cb)
; #pragma unroll
;     for (int g = 0; g < 4; ++g) ggv[cb * 4 + g] = *(const u32x2*)(grow + 32 * cb + 8 * g + 4 * hi);
;   __builtin_amdgcn_sched_barrier(0);
; #pragma unroll
;   for (int cb = 0; cb < NCB; ++cb)
; #pragma unroll
;     for (int g = 0; g < 4; ++g) {
;       const int dv = 32 * cb + 8 * g + 4 * hi;
;       const u32x2 gg = ggv[cb * 4 + g];
;       float gv[4] = {bf2f(gg[0] & 0xffffu), bf2f(gg[0] >> 16), bf2f(gg[1] & 0xffffu), bf2f(gg[1] >> 16)};
;       float ov[4];
; #pragma unroll
;       for (int j = 0; j < 4; ++j) {
;         const float sg = gv[j] * __builtin_amdgcn_rcpf(1.f + __builtin_amdgcn_exp2f(-LOG2E * gv[j]));
;         ov[j] = o[cb][4 * g + j] * inv * sg;
;       }
;       *(unsigned*)((unsigned char*)yrow + dv) = pk4_fp8(ov[0] * Y_SCALE, ov[1] * Y_SCALE, ov[2] * Y_SCALE, ov[3] * Y_SCALE);
;       __builtin_amdgcn_sched_barrier(0);
;     }
	v_mfma_f32_32x32x16_bf16 v[2:17], v[66:69], v[34:37], v[2:17]
	v_mov_b32_e32 v34, v38
	s_nop 1
	v_permlane32_swap_b32_e32 v38, v34
	v_mov_b32_e32 v35, v1
	v_mfma_f32_32x32x16_bf16 v[2:17], v[62:65], v[42:45], v[2:17]
	v_mfma_f32_32x32x16_bf16 v[2:17], v[58:61], v[46:49], v[2:17]
	v_mfma_f32_32x32x16_bf16 v[2:17], v[54:57], v[50:53], v[2:17]
	v_add_f32_e32 v54, v38, v34
	v_lshlrev_b32_e32 v34, 1, v82
	v_lshl_add_u64 v[34:35], v[84:85], 0, v[34:35]
	v_lshl_add_u64 v[50:51], v[34:35], 0, s[0:1]
	s_movk_i32 s0, 0x1000
	v_add_co_u32_e32 v34, vcc, s0, v34
	s_nop 1
	v_addc_co_u32_e32 v35, vcc, 0, v35, vcc
	global_load_dwordx2 v[52:53], v[34:35], off offset:3072
	global_load_dwordx2 v[48:49], v[50:51], off offset:16
	global_load_dwordx2 v[46:47], v[50:51], off offset:32
	global_load_dwordx2 v[44:45], v[50:51], off offset:48
	global_load_dwordx2 v[42:43], v[50:51], off offset:64
	global_load_dwordx2 v[38:39], v[50:51], off offset:80
	global_load_dwordx2 v[36:37], v[50:51], off offset:96
	global_load_dwordx2 v[34:35], v[50:51], off offset:112
	v_rcp_f32_e32 v50, v54
	s_waitcnt vmcnt(7)
	v_lshlrev_b32_e32 v51, 16, v52
	v_mul_f32_e32 v55, 0xbfb8aa3b, v51
	v_exp_f32_e32 v55, v55
	v_and_b32_e32 v52, 0xffff0000, v52
	v_mul_f32_e32 v18, v18, v50
	v_lshlrev_b32_e32 v54, 16, v53
	v_add_f32_e32 v55, 1.0, v55
	v_rcp_f32_e32 v55, v55
	v_mul_f32_e32 v19, v19, v50
	v_and_b32_e32 v53, 0xffff0000, v53
	v_mul_f32_e32 v20, v20, v50
	v_mul_f32_e32 v51, v55, v51
	v_mul_f32_e32 v18, v18, v51
	v_mul_f32_e32 v51, 0xbfb8aa3b, v52
	v_exp_f32_e32 v51, v51
	v_mul_f32_e32 v21, v21, v50
	v_mul_f32_e32 v18, 0x41800000, v18
	v_med3_f32 v18, v18, s93, v223
	v_add_f32_e32 v51, 1.0, v51
	v_rcp_f32_e32 v51, v51
	s_nop 0
	v_mul_f32_e32 v51, v51, v52
	v_mul_f32_e32 v19, v19, v51
	v_mul_f32_e32 v51, 0xbfb8aa3b, v54
	v_exp_f32_e32 v51, v51
	v_mul_f32_e32 v19, 0x41800000, v19
	v_med3_f32 v19, v19, s93, v223
	v_add_f32_e32 v51, 1.0, v51
	v_rcp_f32_e32 v51, v51
	s_nop 0
	v_mul_f32_e32 v51, v51, v54
	v_mul_f32_e32 v20, v20, v51
	v_mul_f32_e32 v51, 0xbfb8aa3b, v53
	v_exp_f32_e32 v51, v51
	v_mul_f32_e32 v20, 0x41800000, v20
	v_add_f32_e32 v51, 1.0, v51
	v_rcp_f32_e32 v51, v51
	s_nop 0
	v_mul_f32_e32 v51, v51, v53
	v_mul_f32_e32 v21, v21, v51
	v_mov_b32_e32 v212, v1
	v_cvt_pk_fp8_f32 v212, v18, v19
	v_mul_f32_e32 v21, 0x41800000, v21
	v_med3_f32 v18, v20, s93, v223
	v_med3_f32 v19, v21, s93, v223
	v_cvt_pk_fp8_f32 v212, v18, v19 op_sel:[0,0,1]
	v_lshl_add_u64 v[18:19], v[40:41], 0, v[82:83]
	s_waitcnt vmcnt(6)
	v_lshlrev_b32_e32 v20, 16, v48
	v_and_b32_e32 v21, 0xffff0000, v48
	v_mul_f32_e32 v48, 0xbfb8aa3b, v20
	v_exp_f32_e32 v48, v48
	v_mul_f32_e32 v22, v22, v50
	v_lshlrev_b32_e32 v40, 16, v49
	v_and_b32_e32 v41, 0xffff0000, v49
	v_add_f32_e32 v48, 1.0, v48
	v_rcp_f32_e32 v48, v48
	s_nop 0
	v_mul_f32_e32 v20, v48, v20
	v_mul_f32_e32 v20, v22, v20
	v_mul_f32_e32 v22, 0xbfb8aa3b, v21
	v_exp_f32_e32 v22, v22
	v_mul_f32_e32 v20, 0x41800000, v20
	v_med3_f32 v20, v20, s93, v223
	v_add_f32_e32 v22, 1.0, v22
	v_rcp_f32_e32 v22, v22
	s_nop 0
	v_mul_f32_e32 v21, v22, v21
	v_mul_f32_e32 v22, v23, v50
	v_mul_f32_e32 v21, v22, v21
	v_mul_f32_e32 v22, 0xbfb8aa3b, v40
	v_exp_f32_e32 v22, v22
	v_mul_f32_e32 v23, v24, v50
	v_mul_f32_e32 v24, v25, v50
	v_mul_f32_e32 v21, 0x41800000, v21
	v_add_f32_e32 v22, 1.0, v22
	v_rcp_f32_e32 v22, v22
	v_med3_f32 v21, v21, s93, v223
	v_mul_f32_e32 v22, v22, v40
	v_mul_f32_e32 v22, v23, v22
	v_mul_f32_e32 v23, 0xbfb8aa3b, v41
	v_exp_f32_e32 v23, v23
	v_mul_f32_e32 v22, 0x41800000, v22
	v_add_f32_e32 v23, 1.0, v23
	v_rcp_f32_e32 v23, v23
	s_nop 0
	v_mul_f32_e32 v23, v23, v41
	v_mul_f32_e32 v23, v24, v23
	v_mov_b32_e32 v214, v1
	v_cvt_pk_fp8_f32 v214, v20, v21
	v_mul_f32_e32 v23, 0x41800000, v23
	v_med3_f32 v20, v22, s93, v223
	v_med3_f32 v21, v23, s93, v223
	v_cvt_pk_fp8_f32 v214, v20, v21 op_sel:[0,0,1]
	s_waitcnt vmcnt(5)
	v_lshlrev_b32_e32 v20, 16, v46
	v_mul_f32_e32 v24, 0xbfb8aa3b, v20
	v_exp_f32_e32 v24, v24
	v_and_b32_e32 v21, 0xffff0000, v46
	v_lshlrev_b32_e32 v22, 16, v47
	v_and_b32_e32 v23, 0xffff0000, v47
	v_add_f32_e32 v24, 1.0, v24
	v_rcp_f32_e32 v24, v24
	s_nop 0
	v_mul_f32_e32 v20, v24, v20
	v_mul_f32_e32 v24, v26, v50
	v_mul_f32_e32 v20, v24, v20
	v_mul_f32_e32 v24, 0xbfb8aa3b, v21
	v_exp_f32_e32 v24, v24
	v_mul_f32_e32 v20, 0x41800000, v20
	v_med3_f32 v20, v20, s93, v223
	v_add_f32_e32 v24, 1.0, v24
	v_rcp_f32_e32 v24, v24
	s_nop 0
	v_mul_f32_e32 v21, v24, v21
	v_mul_f32_e32 v24, v27, v50
	v_mul_f32_e32 v21, v24, v21
	v_mul_f32_e32 v24, 0xbfb8aa3b, v22
	v_exp_f32_e32 v24, v24
	v_mul_f32_e32 v21, 0x41800000, v21
	v_med3_f32 v21, v21, s93, v223
	v_add_f32_e32 v24, 1.0, v24
	v_rcp_f32_e32 v24, v24
	s_nop 0
	v_mul_f32_e32 v22, v24, v22
	v_mul_f32_e32 v24, v28, v50
	v_mul_f32_e32 v22, v24, v22
	v_mul_f32_e32 v24, 0xbfb8aa3b, v23
	v_exp_f32_e32 v24, v24
	v_mul_f32_e32 v22, 0x41800000, v22
	v_add_f32_e32 v24, 1.0, v24
	v_rcp_f32_e32 v24, v24
	s_nop 0
	v_mul_f32_e32 v23, v24, v23
	v_mul_f32_e32 v24, v29, v50
	v_mul_f32_e32 v23, v24, v23
	v_mov_b32_e32 v213, v1
	v_cvt_pk_fp8_f32 v213, v20, v21
	v_mul_f32_e32 v23, 0x41800000, v23
	v_med3_f32 v20, v22, s93, v223
	v_med3_f32 v21, v23, s93, v223
	v_cvt_pk_fp8_f32 v213, v20, v21 op_sel:[0,0,1]
	s_waitcnt vmcnt(4)
; DI float bf2f(unsigned b) { return __uint_as_float(b << 16); }
; template <int DQK, int W1, int DV, int VW, int MODE> ...
;     ...
; #pragma unroll
;   for (int cb = 0; cb < NCB; ++cb)
; #pragma unroll
;     for (int g = 0; g < 4; ++g) {
;       const int dv = 32 * cb + 8 * g + 4 * hi;
;       const u32x2 gg = ggv[cb * 4 + g];
;       float gv[4] = {bf2f(gg[0] & 0xffffu), bf2f(gg[0] >> 16), bf2f(gg[1] & 0xffffu), bf2f(gg[1] >> 16)};
;       float ov[4];
; #pragma unroll
;       for (int j = 0; j < 4; ++j) {
;         const float sg = gv[j] * __builtin_amdgcn_rcpf(1.f + __builtin_amdgcn_exp2f(-LOG2E * gv[j]));
;         ov[j] = o[cb][4 * g + j] * inv * sg;
;       }
;       *(unsigned*)((unsigned char*)yrow + dv) = pk4_fp8(ov[0] * Y_SCALE, ov[1] * Y_SCALE, ov[2] * Y_SCALE, ov[3] * Y_SCALE);
;       __builtin_amdgcn_sched_barrier(0);
;     }
	v_lshlrev_b32_e32 v20, 16, v44
	v_mul_f32_e32 v24, 0xbfb8aa3b, v20
	v_exp_f32_e32 v24, v24
	v_and_b32_e32 v21, 0xffff0000, v44
	v_lshlrev_b32_e32 v22, 16, v45
	v_and_b32_e32 v23, 0xffff0000, v45
	v_add_f32_e32 v24, 1.0, v24
	v_rcp_f32_e32 v24, v24
	s_nop 0
	v_mul_f32_e32 v20, v24, v20
	v_mul_f32_e32 v24, v30, v50
	v_mul_f32_e32 v20, v24, v20
	v_mul_f32_e32 v24, 0xbfb8aa3b, v21
	v_exp_f32_e32 v24, v24
	v_mul_f32_e32 v20, 0x41800000, v20
	v_med3_f32 v20, v20, s93, v223
	v_add_f32_e32 v24, 1.0, v24
	v_rcp_f32_e32 v24, v24
	s_nop 0
	v_mul_f32_e32 v21, v24, v21
	v_mul_f32_e32 v24, v31, v50
	v_mul_f32_e32 v21, v24, v21
	v_mul_f32_e32 v24, 0xbfb8aa3b, v22
	v_exp_f32_e32 v24, v24
	v_mul_f32_e32 v21, 0x41800000, v21
	v_med3_f32 v21, v21, s93, v223
	v_add_f32_e32 v24, 1.0, v24
	v_rcp_f32_e32 v24, v24
	s_nop 0
	v_mul_f32_e32 v22, v24, v22
	v_mul_f32_e32 v24, v32, v50
	v_mul_f32_e32 v22, v24, v22
	v_mul_f32_e32 v24, 0xbfb8aa3b, v23
	v_exp_f32_e32 v24, v24
	v_mul_f32_e32 v22, 0x41800000, v22
	v_add_f32_e32 v24, 1.0, v24
	v_rcp_f32_e32 v24, v24
	s_nop 0
	v_mul_f32_e32 v23, v24, v23
	v_mul_f32_e32 v24, v33, v50
	v_mul_f32_e32 v23, v24, v23
	v_mov_b32_e32 v215, v1
	v_cvt_pk_fp8_f32 v215, v20, v21
	v_mul_f32_e32 v23, 0x41800000, v23
	v_med3_f32 v20, v22, s93, v223
	v_med3_f32 v21, v23, s93, v223
	v_cvt_pk_fp8_f32 v215, v20, v21 op_sel:[0,0,1]
	v_and_b32_e32 v242, 32, v179
	v_lshrrev_b32_e32 v242, 3, v242
	v_lshl_add_u32 v242, v242, 1, v242
	v_mov_b32_e32 v243, 0
	v_lshl_add_u64 v[216:217], v[18:19], 0, v[242:243]
	s_nop 1
	v_permlane32_swap_b32_e32 v212, v213
	v_permlane32_swap_b32_e32 v214, v215
	global_store_dwordx4 v[216:217], v[212:215], off
	s_waitcnt vmcnt(4)
	v_lshlrev_b32_e32 v20, 16, v42
	v_mul_f32_e32 v24, 0xbfb8aa3b, v20
	v_exp_f32_e32 v24, v24
	v_and_b32_e32 v21, 0xffff0000, v42
	v_mul_f32_e32 v2, v2, v50
	v_lshlrev_b32_e32 v22, 16, v43
	v_add_f32_e32 v24, 1.0, v24
	v_rcp_f32_e32 v24, v24
	v_mul_f32_e32 v3, v3, v50
	v_and_b32_e32 v23, 0xffff0000, v43
	v_mul_f32_e32 v4, v4, v50
	v_mul_f32_e32 v20, v24, v20
	v_mul_f32_e32 v2, v2, v20
	v_mul_f32_e32 v20, 0xbfb8aa3b, v21
	v_exp_f32_e32 v20, v20
	v_mul_f32_e32 v5, v5, v50
	v_mul_f32_e32 v2, 0x41800000, v2
	v_med3_f32 v2, v2, s93, v223
	v_add_f32_e32 v20, 1.0, v20
	v_rcp_f32_e32 v20, v20
	s_nop 0
	v_mul_f32_e32 v20, v20, v21
	v_mul_f32_e32 v3, v3, v20
	v_mul_f32_e32 v20, 0xbfb8aa3b, v22
	v_exp_f32_e32 v20, v20
	v_mul_f32_e32 v3, 0x41800000, v3
	v_med3_f32 v3, v3, s93, v223
	v_add_f32_e32 v20, 1.0, v20
	v_rcp_f32_e32 v20, v20
	s_nop 0
	v_mul_f32_e32 v20, v20, v22
	v_mul_f32_e32 v4, v4, v20
	v_mul_f32_e32 v20, 0xbfb8aa3b, v23
	v_exp_f32_e32 v20, v20
	v_mul_f32_e32 v4, 0x41800000, v4
	v_add_f32_e32 v20, 1.0, v20
	v_rcp_f32_e32 v20, v20
	s_nop 0
	v_mul_f32_e32 v20, v20, v23
	v_mul_f32_e32 v5, v5, v20
	v_mov_b32_e32 v212, v1
	v_cvt_pk_fp8_f32 v212, v2, v3
	v_mul_f32_e32 v5, 0x41800000, v5
	v_med3_f32 v2, v4, s93, v223
	v_med3_f32 v3, v5, s93, v223
	v_cvt_pk_fp8_f32 v212, v2, v3 op_sel:[0,0,1]
	s_waitcnt vmcnt(3)
	v_lshlrev_b32_e32 v2, 16, v38
	v_mul_f32_e32 v20, 0xbfb8aa3b, v2
	v_exp_f32_e32 v20, v20
	v_and_b32_e32 v3, 0xffff0000, v38
	v_mul_f32_e32 v6, v6, v50
	v_lshlrev_b32_e32 v4, 16, v39
	v_add_f32_e32 v20, 1.0, v20
	v_rcp_f32_e32 v20, v20
	v_and_b32_e32 v5, 0xffff0000, v39
	v_mul_f32_e32 v2, v20, v2
	v_mul_f32_e32 v2, v6, v2
	v_mul_f32_e32 v6, 0xbfb8aa3b, v3
	v_exp_f32_e32 v6, v6
	v_mul_f32_e32 v2, 0x41800000, v2
	v_med3_f32 v2, v2, s93, v223
	v_add_f32_e32 v6, 1.0, v6
	v_rcp_f32_e32 v6, v6
	s_nop 0
	v_mul_f32_e32 v3, v6, v3
	v_mul_f32_e32 v6, v7, v50
	v_mul_f32_e32 v3, v6, v3
	v_mul_f32_e32 v6, 0xbfb8aa3b, v4
	v_exp_f32_e32 v6, v6
	v_mul_f32_e32 v3, 0x41800000, v3
	v_med3_f32 v3, v3, s93, v223
	v_add_f32_e32 v6, 1.0, v6
	v_rcp_f32_e32 v6, v6
	s_nop 0
	v_mul_f32_e32 v4, v6, v4
	v_mul_f32_e32 v6, v8, v50
	v_mul_f32_e32 v4, v6, v4
	v_mul_f32_e32 v6, 0xbfb8aa3b, v5
	v_exp_f32_e32 v6, v6
	v_mul_f32_e32 v4, 0x41800000, v4
	v_add_f32_e32 v6, 1.0, v6
	v_rcp_f32_e32 v6, v6
	s_nop 0
	v_mul_f32_e32 v5, v6, v5
	v_mul_f32_e32 v6, v9, v50
	v_mul_f32_e32 v5, v6, v5
	v_mov_b32_e32 v214, v1
	v_cvt_pk_fp8_f32 v214, v2, v3
	v_mul_f32_e32 v5, 0x41800000, v5
	v_med3_f32 v2, v4, s93, v223
	v_med3_f32 v3, v5, s93, v223
	v_cvt_pk_fp8_f32 v214, v2, v3 op_sel:[0,0,1]
	s_waitcnt vmcnt(2)
	v_lshlrev_b32_e32 v2, 16, v36
	v_mul_f32_e32 v6, 0xbfb8aa3b, v2
	v_exp_f32_e32 v6, v6
	v_and_b32_e32 v3, 0xffff0000, v36
	v_lshlrev_b32_e32 v4, 16, v37
	v_and_b32_e32 v5, 0xffff0000, v37
	v_add_f32_e32 v6, 1.0, v6
	v_rcp_f32_e32 v6, v6
	s_nop 0
	v_mul_f32_e32 v2, v6, v2
	v_mul_f32_e32 v6, v10, v50
	v_mul_f32_e32 v2, v6, v2
	v_mul_f32_e32 v6, 0xbfb8aa3b, v3
	v_exp_f32_e32 v6, v6
	v_mul_f32_e32 v2, 0x41800000, v2
	v_med3_f32 v2, v2, s93, v223
	v_add_f32_e32 v6, 1.0, v6
	v_rcp_f32_e32 v6, v6
	s_nop 0
	v_mul_f32_e32 v3, v6, v3
	v_mul_f32_e32 v6, v11, v50
	v_mul_f32_e32 v3, v6, v3
	v_mul_f32_e32 v6, 0xbfb8aa3b, v4
	v_exp_f32_e32 v6, v6
	v_mul_f32_e32 v3, 0x41800000, v3
	v_med3_f32 v3, v3, s93, v223
	v_add_f32_e32 v6, 1.0, v6
	v_rcp_f32_e32 v6, v6
	s_nop 0
	v_mul_f32_e32 v4, v6, v4
	v_mul_f32_e32 v6, v12, v50
	v_mul_f32_e32 v4, v6, v4
	v_mul_f32_e32 v6, 0xbfb8aa3b, v5
	v_exp_f32_e32 v6, v6
	v_mul_f32_e32 v4, 0x41800000, v4
	v_add_f32_e32 v6, 1.0, v6
	v_rcp_f32_e32 v6, v6
	s_nop 0
	v_mul_f32_e32 v5, v6, v5
	v_mul_f32_e32 v6, v13, v50
	v_mul_f32_e32 v5, v6, v5
	v_mov_b32_e32 v213, v1
	v_cvt_pk_fp8_f32 v213, v2, v3
	v_mul_f32_e32 v5, 0x41800000, v5
	v_med3_f32 v2, v4, s93, v223
	v_med3_f32 v3, v5, s93, v223
	v_cvt_pk_fp8_f32 v213, v2, v3 op_sel:[0,0,1]
	s_waitcnt vmcnt(1)
	v_lshlrev_b32_e32 v2, 16, v34
	v_mul_f32_e32 v6, 0xbfb8aa3b, v2
	v_exp_f32_e32 v6, v6
	v_and_b32_e32 v3, 0xffff0000, v34
	v_lshlrev_b32_e32 v4, 16, v35
	v_and_b32_e32 v5, 0xffff0000, v35
	v_add_f32_e32 v6, 1.0, v6
	v_rcp_f32_e32 v6, v6
	s_nop 0
	v_mul_f32_e32 v2, v6, v2
	v_mul_f32_e32 v6, v14, v50
	v_mul_f32_e32 v2, v6, v2
	v_mul_f32_e32 v6, 0xbfb8aa3b, v3
	v_exp_f32_e32 v6, v6
	v_mul_f32_e32 v2, 0x41800000, v2
	v_med3_f32 v2, v2, s93, v223
	v_add_f32_e32 v6, 1.0, v6
	v_rcp_f32_e32 v6, v6
	s_nop 0
	v_mul_f32_e32 v3, v6, v3
	v_mul_f32_e32 v6, v15, v50
	v_mul_f32_e32 v3, v6, v3
	v_mul_f32_e32 v6, 0xbfb8aa3b, v4
	v_exp_f32_e32 v6, v6
	v_mul_f32_e32 v3, 0x41800000, v3
	v_med3_f32 v3, v3, s93, v223
	v_add_f32_e32 v6, 1.0, v6
	v_rcp_f32_e32 v6, v6
	s_nop 0
	v_mul_f32_e32 v4, v6, v4
	v_mul_f32_e32 v6, v16, v50
	v_mul_f32_e32 v4, v6, v4
	v_mul_f32_e32 v6, 0xbfb8aa3b, v5
	v_exp_f32_e32 v6, v6
	v_mul_f32_e32 v4, 0x41800000, v4
	v_add_f32_e32 v6, 1.0, v6
	v_rcp_f32_e32 v6, v6
	s_nop 0
	v_mul_f32_e32 v5, v6, v5
	v_mul_f32_e32 v6, v17, v50
	v_mul_f32_e32 v5, v6, v5
	v_mov_b32_e32 v215, v1
	v_cvt_pk_fp8_f32 v215, v2, v3
	v_mul_f32_e32 v5, 0x41800000, v5
	v_med3_f32 v2, v4, s93, v223
	v_med3_f32 v3, v5, s93, v223
	v_cvt_pk_fp8_f32 v215, v2, v3 op_sel:[0,0,1]
	s_nop 1
	v_permlane32_swap_b32_e32 v212, v213
	v_permlane32_swap_b32_e32 v214, v215
	global_store_dwordx4 v[216:217], v[212:215], off offset:32
	s_mov_b64 s[0:1], 0

; DI float bf2f(unsigned b) { return __uint_as_float(b << 16); }
; template <int DQK, int W1, int DV, int VW, int MODE> ...
;     ...
;   const float inv = __builtin_amdgcn_rcpf(xhalf_sum(l));
;   u32x2 ggv[NCB * 4];
; #pragma unroll
;   for (int cb = 0; cb < NCB; ++cb)
; #pragma unroll
;     for (int g = 0; g < 4; ++g) ggv[cb * 4 + g] = *(const u32x2*)(grow + 32 * cb + 8 * g + 4 * hi);
;   __builtin_amdgcn_sched_barrier(0);
; #pragma unroll
;   for (int cb = 0; cb < NCB; ++cb)
; #pragma unroll
;     for (int g = 0; g < 4; ++g) {
;       const int dv = 32 * cb + 8 * g + 4 * hi;
;       const u32x2 gg = ggv[cb * 4 + g];
;       float gv[4] = {bf2f(gg[0] & 0xffffu), bf2f(gg[0] >> 16), bf2f(gg[1] & 0xffffu), bf2f(gg[1] >> 16)};
;       float ov[4];
; #pragma unroll
;       for (int j = 0; j < 4; ++j) {
;         const float sg = gv[j] * __builtin_amdgcn_rcpf(1.f + __builtin_amdgcn_exp2f(-LOG2E * gv[j]));
;         ov[j] = o[cb][4 * g + j] * inv * sg;
;       }
;       *(unsigned*)((unsigned char*)yrow + dv) = pk4_fp8(ov[0] * Y_SCALE, ov[1] * Y_SCALE, ov[2] * Y_SCALE, ov[3] * Y_SCALE);
;       __builtin_amdgcn_sched_barrier(0);
;     }
.LBB0_1348:
	v_mov_b64_e32 v[34:35], s[82:83]
	v_mov_b32_e32 v0, v119
	v_mad_u64_u32 v[34:35], s[0:1], v86, s34, v[34:35]
	s_nop 0
	v_permlane32_swap_b32_e32 v119, v0
	v_mad_i32_i24 v35, v87, s34, v35
	v_add_f32_e32 v54, v119, v0
	v_lshlrev_b32_e32 v0, 1, v82
	v_lshl_add_u64 v[46:47], v[34:35], 0, s[10:11]
	v_lshl_add_u64 v[34:35], v[84:85], 0, v[0:1]
	s_mov_b64 s[0:1], 0x24a0
	v_lshl_add_u64 v[48:49], v[34:35], 0, s[0:1]
	s_movk_i32 s0, 0x2000
	v_add_co_u32_e32 v34, vcc, s0, v34
	v_mov_b32_e32 v83, v1
	s_nop 0
	v_addc_co_u32_e32 v35, vcc, 0, v35, vcc
	global_load_dwordx2 v[50:51], v[34:35], off offset:1184
	global_load_dwordx2 v[52:53], v[48:49], off offset:16
	global_load_dwordx2 v[44:45], v[48:49], off offset:32
	global_load_dwordx2 v[42:43], v[48:49], off offset:48
	global_load_dwordx2 v[40:41], v[48:49], off offset:64
	global_load_dwordx2 v[38:39], v[48:49], off offset:80
	global_load_dwordx2 v[36:37], v[48:49], off offset:96
	global_load_dwordx2 v[34:35], v[48:49], off offset:112
	v_rcp_f32_e32 v0, v54
	s_waitcnt vmcnt(7)
	v_lshlrev_b32_e32 v48, 16, v50
	v_mul_f32_e32 v54, 0xbfb8aa3b, v48
	v_exp_f32_e32 v54, v54
	v_and_b32_e32 v49, 0xffff0000, v50
	v_mul_f32_e32 v18, v18, v0
	v_lshlrev_b32_e32 v50, 16, v51
	v_add_f32_e32 v54, 1.0, v54
	v_rcp_f32_e32 v54, v54
	v_mul_f32_e32 v19, v19, v0
	v_and_b32_e32 v51, 0xffff0000, v51
	v_mul_f32_e32 v20, v20, v0
	v_mul_f32_e32 v48, v54, v48
	v_mul_f32_e32 v18, v18, v48
	v_mul_f32_e32 v48, 0xbfb8aa3b, v49
	v_exp_f32_e32 v48, v48
	v_mul_f32_e32 v21, v21, v0
	v_mul_f32_e32 v18, 0x41800000, v18
	v_med3_f32 v18, v18, s93, v223
	v_add_f32_e32 v48, 1.0, v48
	v_rcp_f32_e32 v48, v48
	s_nop 0
	v_mul_f32_e32 v48, v48, v49
	v_mul_f32_e32 v19, v19, v48
	v_mul_f32_e32 v48, 0xbfb8aa3b, v50
	v_exp_f32_e32 v48, v48
	v_mul_f32_e32 v19, 0x41800000, v19
	v_med3_f32 v19, v19, s93, v223
	v_add_f32_e32 v48, 1.0, v48
	v_rcp_f32_e32 v48, v48
	s_nop 0
	v_mul_f32_e32 v48, v48, v50
	v_mul_f32_e32 v20, v20, v48
	v_mul_f32_e32 v48, 0xbfb8aa3b, v51
	v_exp_f32_e32 v48, v48
	v_mul_f32_e32 v20, 0x41800000, v20
	v_add_f32_e32 v48, 1.0, v48
	v_rcp_f32_e32 v48, v48
	s_nop 0
	v_mul_f32_e32 v48, v48, v51
	v_mul_f32_e32 v21, v21, v48
	v_mov_b32_e32 v212, v1
	v_cvt_pk_fp8_f32 v212, v18, v19
	v_mul_f32_e32 v21, 0x41800000, v21
	v_med3_f32 v18, v20, s93, v223
	v_med3_f32 v19, v21, s93, v223
	v_cvt_pk_fp8_f32 v212, v18, v19 op_sel:[0,0,1]
	v_lshl_add_u64 v[18:19], v[46:47], 0, v[82:83]
	s_waitcnt vmcnt(6)
	v_lshlrev_b32_e32 v20, 16, v52
	v_mul_f32_e32 v48, 0xbfb8aa3b, v20
	v_exp_f32_e32 v48, v48
	v_and_b32_e32 v21, 0xffff0000, v52
	v_mul_f32_e32 v22, v22, v0
	v_lshlrev_b32_e32 v46, 16, v53
	v_add_f32_e32 v48, 1.0, v48
	v_rcp_f32_e32 v48, v48
	v_and_b32_e32 v47, 0xffff0000, v53
	v_mul_f32_e32 v20, v48, v20
	v_mul_f32_e32 v20, v22, v20
	v_mul_f32_e32 v22, 0xbfb8aa3b, v21
	v_exp_f32_e32 v22, v22
	v_mul_f32_e32 v20, 0x41800000, v20
	v_med3_f32 v20, v20, s93, v223
	v_add_f32_e32 v22, 1.0, v22
	v_rcp_f32_e32 v22, v22
	s_nop 0
	v_mul_f32_e32 v21, v22, v21
	v_mul_f32_e32 v22, v23, v0
	v_mul_f32_e32 v21, v22, v21
	v_mul_f32_e32 v22, 0xbfb8aa3b, v46
	v_exp_f32_e32 v22, v22
	v_mul_f32_e32 v23, v24, v0
	v_mul_f32_e32 v24, v25, v0
	v_mul_f32_e32 v21, 0x41800000, v21
	v_add_f32_e32 v22, 1.0, v22
	v_rcp_f32_e32 v22, v22
	v_med3_f32 v21, v21, s93, v223
	v_mul_f32_e32 v22, v22, v46
	v_mul_f32_e32 v22, v23, v22
	v_mul_f32_e32 v23, 0xbfb8aa3b, v47
	v_exp_f32_e32 v23, v23
	v_mul_f32_e32 v22, 0x41800000, v22
	v_add_f32_e32 v23, 1.0, v23
	v_rcp_f32_e32 v23, v23
	s_nop 0
	v_mul_f32_e32 v23, v23, v47
	v_mul_f32_e32 v23, v24, v23
	v_mov_b32_e32 v214, v1
	v_cvt_pk_fp8_f32 v214, v20, v21
	v_mul_f32_e32 v23, 0x41800000, v23
	v_med3_f32 v20, v22, s93, v223
	v_med3_f32 v21, v23, s93, v223
	v_cvt_pk_fp8_f32 v214, v20, v21 op_sel:[0,0,1]
	s_waitcnt vmcnt(5)
	v_lshlrev_b32_e32 v20, 16, v44
	v_mul_f32_e32 v24, 0xbfb8aa3b, v20
	v_exp_f32_e32 v24, v24
	v_and_b32_e32 v21, 0xffff0000, v44
	v_lshlrev_b32_e32 v22, 16, v45
	v_and_b32_e32 v23, 0xffff0000, v45
	v_add_f32_e32 v24, 1.0, v24
	v_rcp_f32_e32 v24, v24
	s_nop 0
	v_mul_f32_e32 v20, v24, v20
	v_mul_f32_e32 v24, v26, v0
	v_mul_f32_e32 v20, v24, v20
	v_mul_f32_e32 v24, 0xbfb8aa3b, v21
	v_exp_f32_e32 v24, v24
	v_mul_f32_e32 v20, 0x41800000, v20
	v_med3_f32 v20, v20, s93, v223
	v_add_f32_e32 v24, 1.0, v24
	v_rcp_f32_e32 v24, v24
	s_nop 0
	v_mul_f32_e32 v21, v24, v21
	v_mul_f32_e32 v24, v27, v0
	v_mul_f32_e32 v21, v24, v21
	v_mul_f32_e32 v24, 0xbfb8aa3b, v22
	v_exp_f32_e32 v24, v24
	v_mul_f32_e32 v21, 0x41800000, v21
	v_med3_f32 v21, v21, s93, v223
	v_add_f32_e32 v24, 1.0, v24
	v_rcp_f32_e32 v24, v24
	s_nop 0
	v_mul_f32_e32 v22, v24, v22
	v_mul_f32_e32 v24, v28, v0
	v_mul_f32_e32 v22, v24, v22
	v_mul_f32_e32 v24, 0xbfb8aa3b, v23
	v_exp_f32_e32 v24, v24
	v_mul_f32_e32 v22, 0x41800000, v22
	v_add_f32_e32 v24, 1.0, v24
	v_rcp_f32_e32 v24, v24
	s_nop 0
	v_mul_f32_e32 v23, v24, v23
	v_mul_f32_e32 v24, v29, v0
	v_mul_f32_e32 v23, v24, v23
	v_mov_b32_e32 v213, v1
	v_cvt_pk_fp8_f32 v213, v20, v21
	v_mul_f32_e32 v23, 0x41800000, v23
	v_med3_f32 v20, v22, s93, v223
	v_med3_f32 v21, v23, s93, v223
	v_cvt_pk_fp8_f32 v213, v20, v21 op_sel:[0,0,1]
	s_waitcnt vmcnt(4)
; DI float bf2f(unsigned b) { return __uint_as_float(b << 16); }
; template <int DQK, int W1, int DV, int VW, int MODE> ...
;     ...
; #pragma unroll
;   for (int cb = 0; cb < NCB; ++cb)
; #pragma unroll
;     for (int g = 0; g < 4; ++g) {
;       const int dv = 32 * cb + 8 * g + 4 * hi;
;       const u32x2 gg = ggv[cb * 4 + g];
;       float gv[4] = {bf2f(gg[0] & 0xffffu), bf2f(gg[0] >> 16), bf2f(gg[1] & 0xffffu), bf2f(gg[1] >> 16)};
;       float ov[4];
; #pragma unroll
;       for (int j = 0; j < 4; ++j) {
;         const float sg = gv[j] * __builtin_amdgcn_rcpf(1.f + __builtin_amdgcn_exp2f(-LOG2E * gv[j]));
;         ov[j] = o[cb][4 * g + j] * inv * sg;
;       }
;       *(unsigned*)((unsigned char*)yrow + dv) = pk4_fp8(ov[0] * Y_SCALE, ov[1] * Y_SCALE, ov[2] * Y_SCALE, ov[3] * Y_SCALE);
;       __builtin_amdgcn_sched_barrier(0);
;     }
	v_lshlrev_b32_e32 v20, 16, v42
	v_mul_f32_e32 v24, 0xbfb8aa3b, v20
	v_exp_f32_e32 v24, v24
	v_and_b32_e32 v21, 0xffff0000, v42
	v_lshlrev_b32_e32 v22, 16, v43
	v_and_b32_e32 v23, 0xffff0000, v43
	v_add_f32_e32 v24, 1.0, v24
	v_rcp_f32_e32 v24, v24
	s_nop 0
	v_mul_f32_e32 v20, v24, v20
	v_mul_f32_e32 v24, v30, v0
	v_mul_f32_e32 v20, v24, v20
	v_mul_f32_e32 v24, 0xbfb8aa3b, v21
	v_exp_f32_e32 v24, v24
	v_mul_f32_e32 v20, 0x41800000, v20
	v_med3_f32 v20, v20, s93, v223
	v_add_f32_e32 v24, 1.0, v24
	v_rcp_f32_e32 v24, v24
	s_nop 0
	v_mul_f32_e32 v21, v24, v21
	v_mul_f32_e32 v24, v31, v0
	v_mul_f32_e32 v21, v24, v21
	v_mul_f32_e32 v24, 0xbfb8aa3b, v22
	v_exp_f32_e32 v24, v24
	v_mul_f32_e32 v21, 0x41800000, v21
	v_med3_f32 v21, v21, s93, v223
	v_add_f32_e32 v24, 1.0, v24
	v_rcp_f32_e32 v24, v24
	s_nop 0
	v_mul_f32_e32 v22, v24, v22
	v_mul_f32_e32 v24, v32, v0
	v_mul_f32_e32 v22, v24, v22
	v_mul_f32_e32 v24, 0xbfb8aa3b, v23
	v_exp_f32_e32 v24, v24
	v_mul_f32_e32 v22, 0x41800000, v22
	v_add_f32_e32 v24, 1.0, v24
	v_rcp_f32_e32 v24, v24
	s_nop 0
	v_mul_f32_e32 v23, v24, v23
	v_mul_f32_e32 v24, v33, v0
	v_mul_f32_e32 v23, v24, v23
	v_mov_b32_e32 v215, v1
	v_cvt_pk_fp8_f32 v215, v20, v21
	v_mul_f32_e32 v23, 0x41800000, v23
	v_med3_f32 v20, v22, s93, v223
	v_med3_f32 v21, v23, s93, v223
	v_cvt_pk_fp8_f32 v215, v20, v21 op_sel:[0,0,1]
	v_and_b32_e32 v242, 32, v179
	v_lshrrev_b32_e32 v242, 3, v242
	v_lshl_add_u32 v242, v242, 1, v242
	v_mov_b32_e32 v243, 0
	v_lshl_add_u64 v[216:217], v[18:19], 0, v[242:243]
	s_nop 1
	v_permlane32_swap_b32_e32 v212, v213
	v_permlane32_swap_b32_e32 v214, v215
	global_store_dwordx4 v[216:217], v[212:215], off
	s_waitcnt vmcnt(4)
	v_lshlrev_b32_e32 v20, 16, v40
	v_mul_f32_e32 v24, 0xbfb8aa3b, v20
	v_exp_f32_e32 v24, v24
	v_and_b32_e32 v21, 0xffff0000, v40
	v_mul_f32_e32 v2, v2, v0
	v_lshlrev_b32_e32 v22, 16, v41
	v_add_f32_e32 v24, 1.0, v24
	v_rcp_f32_e32 v24, v24
	v_mul_f32_e32 v3, v3, v0
	v_and_b32_e32 v23, 0xffff0000, v41
	v_mul_f32_e32 v4, v4, v0
	v_mul_f32_e32 v20, v24, v20
	v_mul_f32_e32 v2, v2, v20
	v_mul_f32_e32 v20, 0xbfb8aa3b, v21
	v_exp_f32_e32 v20, v20
	v_mul_f32_e32 v5, v5, v0
	v_mul_f32_e32 v2, 0x41800000, v2
	v_med3_f32 v2, v2, s93, v223
	v_add_f32_e32 v20, 1.0, v20
	v_rcp_f32_e32 v20, v20
	s_nop 0
	v_mul_f32_e32 v20, v20, v21
	v_mul_f32_e32 v3, v3, v20
	v_mul_f32_e32 v20, 0xbfb8aa3b, v22
	v_exp_f32_e32 v20, v20
	v_mul_f32_e32 v3, 0x41800000, v3
	v_med3_f32 v3, v3, s93, v223
	v_add_f32_e32 v20, 1.0, v20
	v_rcp_f32_e32 v20, v20
	s_nop 0
	v_mul_f32_e32 v20, v20, v22
	v_mul_f32_e32 v4, v4, v20
	v_mul_f32_e32 v20, 0xbfb8aa3b, v23
	v_exp_f32_e32 v20, v20
	v_mul_f32_e32 v4, 0x41800000, v4
	v_add_f32_e32 v20, 1.0, v20
	v_rcp_f32_e32 v20, v20
	s_nop 0
	v_mul_f32_e32 v20, v20, v23
	v_mul_f32_e32 v5, v5, v20
	v_mov_b32_e32 v212, v1
	v_cvt_pk_fp8_f32 v212, v2, v3
	v_mul_f32_e32 v5, 0x41800000, v5
	v_med3_f32 v2, v4, s93, v223
	v_med3_f32 v3, v5, s93, v223
	v_cvt_pk_fp8_f32 v212, v2, v3 op_sel:[0,0,1]
	s_waitcnt vmcnt(3)
; DI float bf2f(unsigned b) { return __uint_as_float(b << 16); }
; template <int DQK, int W1, int DV, int VW, int MODE> ...
;     ...
; #pragma unroll
;   for (int cb = 0; cb < NCB; ++cb)
; #pragma unroll
;     for (int g = 0; g < 4; ++g) {
;       const int dv = 32 * cb + 8 * g + 4 * hi;
;       const u32x2 gg = ggv[cb * 4 + g];
;       float gv[4] = {bf2f(gg[0] & 0xffffu), bf2f(gg[0] >> 16), bf2f(gg[1] & 0xffffu), bf2f(gg[1] >> 16)};
;       float ov[4];
; #pragma unroll
;       for (int j = 0; j < 4; ++j) {
;         const float sg = gv[j] * __builtin_amdgcn_rcpf(1.f + __builtin_amdgcn_exp2f(-LOG2E * gv[j]));
;         ov[j] = o[cb][4 * g + j] * inv * sg;
;       }
;       *(unsigned*)((unsigned char*)yrow + dv) = pk4_fp8(ov[0] * Y_SCALE, ov[1] * Y_SCALE, ov[2] * Y_SCALE, ov[3] * Y_SCALE);
;       __builtin_amdgcn_sched_barrier(0);
;     }
	v_lshlrev_b32_e32 v2, 16, v38
	v_mul_f32_e32 v20, 0xbfb8aa3b, v2
	v_exp_f32_e32 v20, v20
	v_and_b32_e32 v3, 0xffff0000, v38
	v_mul_f32_e32 v6, v6, v0
	v_lshlrev_b32_e32 v4, 16, v39
	v_add_f32_e32 v20, 1.0, v20
	v_rcp_f32_e32 v20, v20
	v_and_b32_e32 v5, 0xffff0000, v39
	v_mul_f32_e32 v2, v20, v2
	v_mul_f32_e32 v2, v6, v2
	v_mul_f32_e32 v6, 0xbfb8aa3b, v3
	v_exp_f32_e32 v6, v6
	v_mul_f32_e32 v2, 0x41800000, v2
	v_med3_f32 v2, v2, s93, v223
	v_add_f32_e32 v6, 1.0, v6
	v_rcp_f32_e32 v6, v6
	s_nop 0
	v_mul_f32_e32 v3, v6, v3
	v_mul_f32_e32 v6, v7, v0
	v_mul_f32_e32 v3, v6, v3
	v_mul_f32_e32 v6, 0xbfb8aa3b, v4
	v_exp_f32_e32 v6, v6
	v_mul_f32_e32 v3, 0x41800000, v3
	v_med3_f32 v3, v3, s93, v223
	v_add_f32_e32 v6, 1.0, v6
	v_rcp_f32_e32 v6, v6
	s_nop 0
	v_mul_f32_e32 v4, v6, v4
	v_mul_f32_e32 v6, v8, v0
	v_mul_f32_e32 v4, v6, v4
	v_mul_f32_e32 v6, 0xbfb8aa3b, v5
	v_exp_f32_e32 v6, v6
	v_mul_f32_e32 v4, 0x41800000, v4
	v_add_f32_e32 v6, 1.0, v6
	v_rcp_f32_e32 v6, v6
	s_nop 0
	v_mul_f32_e32 v5, v6, v5
	v_mul_f32_e32 v6, v9, v0
	v_mul_f32_e32 v5, v6, v5
	v_mov_b32_e32 v214, v1
	v_cvt_pk_fp8_f32 v214, v2, v3
	v_mul_f32_e32 v5, 0x41800000, v5
	v_med3_f32 v2, v4, s93, v223
	v_med3_f32 v3, v5, s93, v223
	v_cvt_pk_fp8_f32 v214, v2, v3 op_sel:[0,0,1]
	s_waitcnt vmcnt(2)
	v_lshlrev_b32_e32 v2, 16, v36
	v_mul_f32_e32 v6, 0xbfb8aa3b, v2
	v_exp_f32_e32 v6, v6
	v_and_b32_e32 v3, 0xffff0000, v36
	v_lshlrev_b32_e32 v4, 16, v37
	v_and_b32_e32 v5, 0xffff0000, v37
	v_add_f32_e32 v6, 1.0, v6
	v_rcp_f32_e32 v6, v6
	s_nop 0
	v_mul_f32_e32 v2, v6, v2
	v_mul_f32_e32 v6, v10, v0
	v_mul_f32_e32 v2, v6, v2
	v_mul_f32_e32 v6, 0xbfb8aa3b, v3
	v_exp_f32_e32 v6, v6
	v_mul_f32_e32 v2, 0x41800000, v2
	v_med3_f32 v2, v2, s93, v223
	v_add_f32_e32 v6, 1.0, v6
	v_rcp_f32_e32 v6, v6
	s_nop 0
	v_mul_f32_e32 v3, v6, v3
	v_mul_f32_e32 v6, v11, v0
	v_mul_f32_e32 v3, v6, v3
	v_mul_f32_e32 v6, 0xbfb8aa3b, v4
	v_exp_f32_e32 v6, v6
	v_mul_f32_e32 v3, 0x41800000, v3
	v_med3_f32 v3, v3, s93, v223
	v_add_f32_e32 v6, 1.0, v6
	v_rcp_f32_e32 v6, v6
	s_nop 0
	v_mul_f32_e32 v4, v6, v4
	v_mul_f32_e32 v6, v12, v0
	v_mul_f32_e32 v4, v6, v4
	v_mul_f32_e32 v6, 0xbfb8aa3b, v5
	v_exp_f32_e32 v6, v6
	v_mul_f32_e32 v4, 0x41800000, v4
	v_add_f32_e32 v6, 1.0, v6
	v_rcp_f32_e32 v6, v6
	s_nop 0
	v_mul_f32_e32 v5, v6, v5
	v_mul_f32_e32 v6, v13, v0
	v_mul_f32_e32 v5, v6, v5
	v_mov_b32_e32 v213, v1
	v_cvt_pk_fp8_f32 v213, v2, v3
	v_mul_f32_e32 v5, 0x41800000, v5
	v_med3_f32 v2, v4, s93, v223
	v_med3_f32 v3, v5, s93, v223
	v_cvt_pk_fp8_f32 v213, v2, v3 op_sel:[0,0,1]
	s_waitcnt vmcnt(1)
	v_lshlrev_b32_e32 v2, 16, v34
	v_mul_f32_e32 v6, 0xbfb8aa3b, v2
	v_exp_f32_e32 v6, v6
	v_and_b32_e32 v3, 0xffff0000, v34
	v_lshlrev_b32_e32 v4, 16, v35
	v_and_b32_e32 v5, 0xffff0000, v35
	v_add_f32_e32 v6, 1.0, v6
	v_rcp_f32_e32 v6, v6
	s_nop 0
	v_mul_f32_e32 v2, v6, v2
	v_mul_f32_e32 v6, v14, v0
	v_mul_f32_e32 v2, v6, v2
	v_mul_f32_e32 v6, 0xbfb8aa3b, v3
	v_exp_f32_e32 v6, v6
	v_mul_f32_e32 v2, 0x41800000, v2
	v_med3_f32 v2, v2, s93, v223
	v_add_f32_e32 v6, 1.0, v6
	v_rcp_f32_e32 v6, v6
	s_nop 0
	v_mul_f32_e32 v3, v6, v3
	v_mul_f32_e32 v6, v15, v0
	v_mul_f32_e32 v3, v6, v3
	v_mul_f32_e32 v6, 0xbfb8aa3b, v4
	v_exp_f32_e32 v6, v6
	v_mul_f32_e32 v3, 0x41800000, v3
	v_med3_f32 v3, v3, s93, v223
	v_add_f32_e32 v6, 1.0, v6
	v_rcp_f32_e32 v6, v6
	s_nop 0
	v_mul_f32_e32 v4, v6, v4
	v_mul_f32_e32 v6, v16, v0
	v_mul_f32_e32 v4, v6, v4
	v_mul_f32_e32 v6, 0xbfb8aa3b, v5
	v_exp_f32_e32 v6, v6
	v_mul_f32_e32 v0, v17, v0
	v_mul_f32_e32 v4, 0x41800000, v4
	v_add_f32_e32 v6, 1.0, v6
	v_rcp_f32_e32 v6, v6
	s_nop 0
	v_mul_f32_e32 v5, v6, v5
	v_mul_f32_e32 v0, v0, v5
	v_mov_b32_e32 v215, v1
	v_cvt_pk_fp8_f32 v215, v2, v3
	v_mul_f32_e32 v0, 0x41800000, v0
	v_med3_f32 v2, v4, s93, v223
	v_med3_f32 v0, v0, s93, v223
	v_cvt_pk_fp8_f32 v215, v2, v0 op_sel:[0,0,1]
	s_nop 1
	v_permlane32_swap_b32_e32 v212, v213
	v_permlane32_swap_b32_e32 v214, v215
	global_store_dwordx4 v[216:217], v[212:215], off offset:32
	s_movk_i32 s20, 0x600
	s_mov_b32 s86, 0x800000
	s_movk_i32 s87, 0x3fff
	v_readlane_b32 s3, v254, 29
